# adds ret-scan load batching, rope table preload in DA qkv epilogue, DA gain-load batching, rope pos prefetch
# speedup vs baseline: 1.0280x; 1.0115x over previous
; DI void phase_prologue(const Params& p, char* lds) {
;     ...
;   for (size_t li = (size_t)((int)blockIdx.x >> 3) * NT + tid; li < (size_t)S_ * 32 && (int)blockIdx.x < ((int)gridDim.x & ~7); li += (size_t)((int)gridDim.x >> 3) * NT) {
;     const size_t i = (size_t)(blockIdx.x & 7) * ((size_t)S_ * 32) + li;
;     int t = (int)(i >> 5), k = (int)(i & 31);
;     double inv = exp2(-(double)k * (1.0 / 32.0) * L2T);
;     double ang = (double)p.pos[t] * inv; ang -= TWO_PI * rint(ang * (1.0 / TWO_PI));
;     float a = (float)ang; p.cosD[i] = cosf(a); p.sinD[i] = sinf(a);
.LBB0_59:
	s_or_b64 exec, exec, s[6:7]
	s_mov_b64 s[6:7], 0x10000
	v_cmp_gt_u64_e32 vcc, s[6:7], v[2:3]
	s_and_b64 s[6:7], vcc, s[34:35]
	s_and_saveexec_b64 s[14:15], s[6:7]
	s_cbranch_execz .LBB0_70
	s_lshl_b32 s6, s2, 16
	v_and_b32_e32 v1, 31, v66
	s_and_b32 s24, s6, 0x70000
	v_cvt_f64_u32_e32 v[4:5], v1
	s_mov_b32 s6, 0x979a371
	v_ldexp_f64 v[4:5], -v[4:5], -5
	s_mov_b32 s7, 0x402a934f
	v_mul_f64 v[4:5], v[4:5], s[6:7]
	v_rndne_f64_e32 v[6:7], v[4:5]
	s_mov_b32 s6, 0x3b39803f
	v_add_f64 v[8:9], v[4:5], -v[6:7]
	s_mov_b32 s7, 0x3c7abc9e
	v_mul_f64 v[10:11], v[8:9], s[6:7]
	s_mov_b32 s6, 0xfefa39ef
	s_mov_b32 s7, 0x3fe62e42
	v_fmac_f64_e32 v[10:11], s[6:7], v[8:9]
	s_mov_b32 s6, 0x6a5dcb37
	v_mov_b32_e32 v8, 0xfca7ab0c
	v_mov_b32_e32 v9, 0x3e928af3
	s_mov_b32 s7, 0x3e5ade15
	v_fmac_f64_e32 v[8:9], s[6:7], v[10:11]
	v_mov_b32_e32 v12, 0x623fde64
	v_mov_b32_e32 v13, 0x3ec71dee
	v_fmac_f64_e32 v[12:13], v[10:11], v[8:9]
	v_mov_b32_e32 v8, 0x7c89e6b0
	v_mov_b32_e32 v9, 0x3efa0199
	v_fmac_f64_e32 v[8:9], v[10:11], v[12:13]
	v_mov_b32_e32 v12, 0x14761f6e
	v_mov_b32_e32 v13, 0x3f2a01a0
	v_fmac_f64_e32 v[12:13], v[10:11], v[8:9]
	v_mov_b32_e32 v8, 0x1852b7b0
	v_mov_b32_e32 v9, 0x3f56c16c
	v_fmac_f64_e32 v[8:9], v[10:11], v[12:13]
	v_mov_b32_e32 v12, 0x11122322
	v_mov_b32_e32 v13, 0x3f811111
	v_fmac_f64_e32 v[12:13], v[10:11], v[8:9]
	v_mov_b32_e32 v8, 0x555502a1
	v_mov_b32_e32 v9, 0x3fa55555
	v_fmac_f64_e32 v[8:9], v[10:11], v[12:13]
	v_mov_b32_e32 v12, 0x55555511
	v_mov_b32_e32 v13, 0x3fc55555
	v_fmac_f64_e32 v[12:13], v[10:11], v[8:9]
	v_mov_b32_e32 v8, 11
	v_mov_b32_e32 v9, 0x3fe00000
	v_fmac_f64_e32 v[8:9], v[10:11], v[12:13]
	s_mov_b32 s6, 0
	v_fma_f64 v[8:9], v[10:11], v[8:9], 1.0
	s_mov_b32 s7, 0x40900000
	v_fma_f64 v[8:9], v[10:11], v[8:9], 1.0
	v_cvt_i32_f64_e32 v1, v[6:7]
	v_cmp_nlt_f64_e32 vcc, s[6:7], v[4:5]
	s_mov_b32 s6, 0
	s_ashr_i32 s8, s30, 3
	v_ldexp_f64 v[6:7], v[8:9], v1
	v_mov_b32_e32 v1, 0x7ff00000
	s_mov_b32 s7, 0xc090cc00
	s_ashr_i32 s9, s8, 31
	v_cndmask_b32_e32 v1, v1, v7, vcc
	v_cmp_ngt_f64_e64 s[6:7], s[6:7], v[4:5]
	s_lshl_b64 s[26:27], s[8:9], 9
	s_and_b64 vcc, s[6:7], vcc
	v_cndmask_b32_e64 v5, 0, v1, s[6:7]
	v_readlane_b32 s6, v253, 2
	v_readlane_b32 s7, v253, 3
	s_add_u32 s6, s24, s6
	s_addc_u32 s7, 0, s7
	v_cndmask_b32_e32 v4, 0, v6, vcc
	v_lshl_add_u64 v[6:7], s[6:7], 0, v[66:67]
	s_mov_b32 s40, 0x6dc9c883
	s_mov_b32 s42, 0x54442d18
	s_mov_b32 s25, 0
	v_lshlrev_b64 v[6:7], 2, v[6:7]
	s_lshl_b64 s[36:37], s[8:9], 11
	s_mov_b64 s[38:39], 0
	s_mov_b32 s41, 0x3fc45f30
	s_mov_b32 s43, 0xc01921fb
	s_brev_b32 s31, 18
	s_mov_b32 s49, 0xfe5163ab
	v_mov_b32_e32 v9, 0
	s_mov_b32 s50, 0x3c439041
	s_mov_b32 s51, 0xdb629599
	s_mov_b32 s52, 0xf534ddc0
	s_mov_b32 s53, 0xfc2757d1
	s_mov_b32 s54, 0x4e441529
	s_mov_b32 s55, 0xa2f9836e
	s_mov_b32 s56, 0x3fc90fda
	s_mov_b32 s57, 0x3f22f983
	s_mov_b32 s58, 0xbfc90fda
	v_mov_b32_e32 v1, 0x3c0881c4
	v_mov_b32_e32 v12, 0xbab64f3b
	s_brev_b32 s59, 1
	s_movk_i32 s60, 0x1f8
	v_mov_b32_e32 v13, 0x7fc00000
	s_mov_b64 s[44:45], 0xffff
	v_not_b32_e32 v14, 63
	v_not_b32_e32 v15, 31
	v_mov_b64_e32 v[10:11], v[2:3]
	v_lshl_add_u64 v[38:39], s[24:25], 0, v[10:11]
	v_lshrrev_b64 v[38:39], 3, v[38:39]
	v_and_b32_e32 v38, -4, v38
	v_lshl_add_u64 v[38:39], s[4:5], 0, v[38:39]
	global_load_dword v36, v[38:39], off
	global_load_dword v37, v[38:39], off
	global_load_dword v40, v[38:39], off
	s_branch .LBB0_62

; DI void phase_prologue(const Params& p, char* lds) {
;     ...
;   for (size_t li = (size_t)((int)blockIdx.x >> 3) * NT + tid; li < (size_t)S_ * 32 && (int)blockIdx.x < ((int)gridDim.x & ~7); li += (size_t)((int)gridDim.x >> 3) * NT) {
;     const size_t i = (size_t)(blockIdx.x & 7) * ((size_t)S_ * 32) + li;
;     int t = (int)(i >> 5), k = (int)(i & 31);
;     double inv = exp2(-(double)k * (1.0 / 32.0) * L2T);
;     double ang = (double)p.pos[t] * inv; ang -= TWO_PI * rint(ang * (1.0 / TWO_PI));
;     float a = (float)ang; p.cosD[i] = cosf(a); p.sinD[i] = sinf(a);
.LBB0_62:
	s_waitcnt vmcnt(2)
	v_mov_b32_e32 v8, v36
	v_lshl_add_u64 v[38:39], v[10:11], 0, s[26:27]
	v_cmp_ge_u64_e32 vcc, s[44:45], v[38:39]
	s_and_saveexec_b64 s[100:101], vcc
	v_lshl_add_u64 v[38:39], s[24:25], 0, v[38:39]
	v_lshrrev_b64 v[38:39], 3, v[38:39]
	v_and_b32_e32 v38, -4, v38
	v_lshl_add_u64 v[38:39], s[4:5], 0, v[38:39]
	global_load_dword v36, v[38:39], off
	s_mov_b64 exec, s[100:101]
	v_cvt_f64_i32_e32 v[16:17], v8
	v_mul_f64 v[16:17], v[4:5], v[16:17]
	v_mul_f64 v[18:19], v[16:17], s[40:41]
	v_rndne_f64_e32 v[18:19], v[18:19]
	v_fmac_f64_e32 v[16:17], s[42:43], v[18:19]
	v_cvt_f32_f64_e32 v16, v[16:17]
	v_and_b32_e32 v17, 0x7fffffff, v16
	v_lshrrev_b32_e32 v8, 23, v17
	v_and_b32_e32 v18, 0x7fffff, v17
	v_cmp_nlt_f32_e64 s[12:13], |v16|, s31
	v_add_u32_e32 v19, 0xffffff88, v8
	v_or_b32_e32 v18, 0x800000, v18
	s_and_saveexec_b64 s[6:7], s[12:13]
	s_xor_b64 s[46:47], exec, s[6:7]
	s_cbranch_execz .LBB0_64
	v_cmp_lt_u32_e32 vcc, 63, v19
	s_nop 1
	v_cndmask_b32_e32 v8, 0, v14, vcc
	v_add_u32_e32 v8, v8, v19
	v_cmp_lt_u32_e64 s[6:7], 31, v8
	s_nop 1
	v_cndmask_b32_e64 v20, 0, v15, s[6:7]
	v_add_u32_e32 v8, v20, v8
	v_cmp_lt_u32_e64 s[8:9], 31, v8
	s_nop 1
	v_cndmask_b32_e64 v20, 0, v15, s[8:9]
	v_add_u32_e32 v34, v20, v8
	v_mad_u64_u32 v[20:21], s[10:11], v18, s49, 0
	v_mov_b32_e32 v8, v21
	v_mad_u64_u32 v[22:23], s[10:11], v18, s50, v[8:9]
	v_mov_b32_e32 v8, v23
	v_mad_u64_u32 v[24:25], s[10:11], v18, s51, v[8:9]
	v_mov_b32_e32 v8, v25
	v_mad_u64_u32 v[26:27], s[10:11], v18, s52, v[8:9]
	v_mov_b32_e32 v8, v27
	v_mad_u64_u32 v[28:29], s[10:11], v18, s53, v[8:9]
	v_mov_b32_e32 v8, v29
	v_mad_u64_u32 v[30:31], s[10:11], v18, s54, v[8:9]
	v_mov_b32_e32 v8, v31
	v_mad_u64_u32 v[32:33], s[10:11], v18, s55, v[8:9]
	v_cndmask_b32_e32 v21, v30, v26, vcc
	v_cndmask_b32_e32 v8, v32, v28, vcc
	v_cndmask_b32_e32 v25, v33, v30, vcc
	v_cndmask_b32_e64 v23, v8, v21, s[6:7]
	v_cndmask_b32_e64 v8, v25, v8, s[6:7]
	v_cndmask_b32_e32 v25, v28, v24, vcc
	v_cndmask_b32_e64 v21, v21, v25, s[6:7]
	v_cndmask_b32_e32 v22, v26, v22, vcc
	v_cndmask_b32_e64 v8, v8, v23, s[8:9]
	v_cndmask_b32_e64 v23, v23, v21, s[8:9]
	v_sub_u32_e32 v27, 32, v34
	v_cndmask_b32_e64 v25, v25, v22, s[6:7]
	v_alignbit_b32 v28, v8, v23, v27
	v_cmp_eq_u32_e64 s[10:11], 0, v34
	v_cndmask_b32_e64 v21, v21, v25, s[8:9]
	v_cndmask_b32_e32 v20, v24, v20, vcc
	v_cndmask_b32_e64 v8, v28, v8, s[10:11]
	v_alignbit_b32 v26, v23, v21, v27
	v_cndmask_b32_e64 v20, v22, v20, s[6:7]
	v_cndmask_b32_e64 v23, v26, v23, s[10:11]
	v_bfe_u32 v29, v8, 29, 1
	v_cndmask_b32_e64 v20, v25, v20, s[8:9]
	v_alignbit_b32 v26, v8, v23, 30
	v_sub_u32_e32 v30, 0, v29
	v_alignbit_b32 v22, v21, v20, v27
	v_xor_b32_e32 v26, v26, v30
	v_cndmask_b32_e64 v21, v22, v21, s[10:11]
	v_alignbit_b32 v22, v23, v21, 30
	v_ffbh_u32_e32 v23, v26
	v_min_u32_e32 v23, 32, v23
	v_alignbit_b32 v20, v21, v20, 30
	v_xor_b32_e32 v22, v22, v30
	v_sub_u32_e32 v24, 31, v23
	v_xor_b32_e32 v20, v20, v30
	v_alignbit_b32 v25, v26, v22, v24
	v_alignbit_b32 v20, v22, v20, v24
	v_alignbit_b32 v21, v25, v20, 9
	v_ffbh_u32_e32 v22, v21
	v_min_u32_e32 v22, 32, v22
	v_lshrrev_b32_e32 v28, 29, v8
	v_not_b32_e32 v24, v22
	v_alignbit_b32 v20, v21, v20, v24
	v_lshlrev_b32_e32 v21, 31, v28
	v_or_b32_e32 v24, 0x33000000, v21
	v_add_lshl_u32 v22, v22, v23, 23
	v_lshrrev_b32_e32 v20, 9, v20
	v_sub_u32_e32 v22, v24, v22
	v_or_b32_e32 v21, 0.5, v21
	v_lshlrev_b32_e32 v23, 23, v23
	v_or_b32_e32 v20, v22, v20
	v_lshrrev_b32_e32 v22, 9, v25
	v_sub_u32_e32 v21, v21, v23
	v_or_b32_e32 v21, v22, v21
	v_mul_f32_e32 v22, 0x3fc90fda, v21
	v_fma_f32 v23, v21, s56, -v22
	v_fmac_f32_e32 v23, 0x33a22168, v21
	v_fmac_f32_e32 v23, 0x3fc90fda, v20
	v_lshrrev_b32_e32 v8, 30, v8
	v_add_f32_e32 v21, v22, v23
	v_add_u32_e32 v20, v29, v8

; DI void phase_prologue(const Params& p, char* lds) {
;     ...
;   for (size_t li = (size_t)((int)blockIdx.x >> 3) * NT + tid; li < (size_t)S_ * 128 && (int)blockIdx.x < ((int)gridDim.x & ~7); li += (size_t)((int)gridDim.x >> 3) * NT) {
;     const size_t i = (size_t)(blockIdx.x & 7) * ((size_t)S_ * 128) + li;
;     int t = (int)(i >> 7), k = (int)(i & 127);
;     double inv = exp2(-(double)k * (1.0 / 127.0) * L2T);
;     double ang = (double)p.pos[t] * inv; ang -= TWO_PI * rint(ang * (1.0 / TWO_PI));
;     float a = (float)ang; p.cosR[i] = cosf(a); p.sinR[i] = sinf(a);
.LBB0_70:
	s_or_b64 exec, exec, s[14:15]
	s_mov_b64 s[6:7], 0x40000
	v_cmp_gt_u64_e32 vcc, s[6:7], v[2:3]
	s_and_b64 s[6:7], vcc, s[34:35]
	s_and_saveexec_b64 s[14:15], s[6:7]
	s_cbranch_execz .LBB0_81
	s_lshl_b32 s6, s2, 18
	s_and_b32 s16, s6, 0x1c0000
	v_and_b32_e32 v1, 0x7f, v66
	s_mov_b32 s6, 0x81020408
	v_cvt_f64_u32_e32 v[4:5], v1
	s_mov_b32 s7, 0xbf802040
	v_mul_f64 v[4:5], v[4:5], s[6:7]
	s_mov_b32 s6, 0x979a371
	s_mov_b32 s7, 0x402a934f
	v_mul_f64 v[4:5], v[4:5], s[6:7]
	v_rndne_f64_e32 v[6:7], v[4:5]
	s_mov_b32 s6, 0x3b39803f
	v_add_f64 v[8:9], v[4:5], -v[6:7]
	s_mov_b32 s7, 0x3c7abc9e
	v_mul_f64 v[10:11], v[8:9], s[6:7]
	s_mov_b32 s6, 0xfefa39ef
	s_mov_b32 s7, 0x3fe62e42
	v_fmac_f64_e32 v[10:11], s[6:7], v[8:9]
	s_mov_b32 s6, 0x6a5dcb37
	v_mov_b32_e32 v8, 0xfca7ab0c
	v_mov_b32_e32 v9, 0x3e928af3
	s_mov_b32 s7, 0x3e5ade15
	v_fmac_f64_e32 v[8:9], s[6:7], v[10:11]
	v_mov_b32_e32 v12, 0x623fde64
	v_mov_b32_e32 v13, 0x3ec71dee
	v_fmac_f64_e32 v[12:13], v[10:11], v[8:9]
	v_mov_b32_e32 v8, 0x7c89e6b0
	v_mov_b32_e32 v9, 0x3efa0199
	v_fmac_f64_e32 v[8:9], v[10:11], v[12:13]
	v_mov_b32_e32 v12, 0x14761f6e
	v_mov_b32_e32 v13, 0x3f2a01a0
	v_fmac_f64_e32 v[12:13], v[10:11], v[8:9]
	v_mov_b32_e32 v8, 0x1852b7b0
	v_mov_b32_e32 v9, 0x3f56c16c
	v_fmac_f64_e32 v[8:9], v[10:11], v[12:13]
	v_mov_b32_e32 v12, 0x11122322
	v_mov_b32_e32 v13, 0x3f811111
	v_fmac_f64_e32 v[12:13], v[10:11], v[8:9]
	v_mov_b32_e32 v8, 0x555502a1
	v_mov_b32_e32 v9, 0x3fa55555
	v_fmac_f64_e32 v[8:9], v[10:11], v[12:13]
	v_mov_b32_e32 v12, 0x55555511
	v_mov_b32_e32 v13, 0x3fc55555
	v_fmac_f64_e32 v[12:13], v[10:11], v[8:9]
	v_mov_b32_e32 v8, 11
	v_mov_b32_e32 v9, 0x3fe00000
	v_fmac_f64_e32 v[8:9], v[10:11], v[12:13]
	s_mov_b32 s6, 0
	v_fma_f64 v[8:9], v[10:11], v[8:9], 1.0
	s_mov_b32 s7, 0x40900000
	v_fma_f64 v[8:9], v[10:11], v[8:9], 1.0
	v_cvt_i32_f64_e32 v1, v[6:7]
	v_cmp_nlt_f64_e32 vcc, s[6:7], v[4:5]
	s_mov_b32 s6, 0
	s_ashr_i32 s8, s30, 3
	v_ldexp_f64 v[6:7], v[8:9], v1
	v_mov_b32_e32 v1, 0x7ff00000
	s_mov_b32 s7, 0xc090cc00
	s_ashr_i32 s9, s8, 31
	v_cndmask_b32_e32 v1, v1, v7, vcc
	v_cmp_ngt_f64_e64 s[6:7], s[6:7], v[4:5]
	s_lshl_b64 s[18:19], s[8:9], 9
	s_and_b64 vcc, s[6:7], vcc
	v_cndmask_b32_e64 v5, 0, v1, s[6:7]
	v_readlane_b32 s6, v253, 2
	v_readlane_b32 s7, v253, 3
	s_add_u32 s6, s16, s6
	s_addc_u32 s7, 0, s7
	v_cndmask_b32_e32 v4, 0, v6, vcc
	v_lshl_add_u64 v[6:7], s[6:7], 0, v[66:67]
	s_mov_b32 s30, 0x6dc9c883
	s_mov_b32 s34, 0x54442d18
	s_mov_b32 s17, 0
	v_lshlrev_b64 v[6:7], 2, v[6:7]
	s_lshl_b64 s[24:25], s[8:9], 11
	s_mov_b64 s[26:27], 0
	s_mov_b32 s31, 0x3fc45f30
	s_mov_b32 s35, 0xc01921fb
	s_brev_b32 s40, 18
	s_mov_b32 s41, 0xfe5163ab
	v_mov_b32_e32 v9, 0
	s_mov_b32 s42, 0x3c439041
	s_mov_b32 s43, 0xdb629599
	s_mov_b32 s44, 0xf534ddc0
	s_mov_b32 s45, 0xfc2757d1
	s_mov_b32 s46, 0x4e441529
	s_mov_b32 s47, 0xa2f9836e
	s_mov_b32 s49, 0x3fc90fda
	s_mov_b32 s50, 0x3f22f983
	s_mov_b32 s51, 0xbfc90fda
	v_mov_b32_e32 v1, 0x3c0881c4
	v_mov_b32_e32 v10, 0xbab64f3b
	s_brev_b32 s52, 1
	s_movk_i32 s53, 0x1f8
	v_mov_b32_e32 v11, 0x7fc00000
	s_mov_b64 s[36:37], 0x3ffff
	v_not_b32_e32 v12, 63
	v_not_b32_e32 v13, 31
	v_lshl_add_u64 v[38:39], s[16:17], 0, v[2:3]
	v_lshrrev_b64 v[38:39], 5, v[38:39]
	v_and_b32_e32 v38, -4, v38
	v_lshl_add_u64 v[38:39], s[4:5], 0, v[38:39]
	global_load_dword v36, v[38:39], off
	global_load_dword v37, v[38:39], off
	global_load_dword v40, v[38:39], off
	s_branch .LBB0_73

; DI void phase_prologue(const Params& p, char* lds) {
;     ...
;   for (size_t li = (size_t)((int)blockIdx.x >> 3) * NT + tid; li < (size_t)S_ * 128 && (int)blockIdx.x < ((int)gridDim.x & ~7); li += (size_t)((int)gridDim.x >> 3) * NT) {
;     const size_t i = (size_t)(blockIdx.x & 7) * ((size_t)S_ * 128) + li;
;     int t = (int)(i >> 7), k = (int)(i & 127);
;     double inv = exp2(-(double)k * (1.0 / 127.0) * L2T);
;     double ang = (double)p.pos[t] * inv; ang -= TWO_PI * rint(ang * (1.0 / TWO_PI));
;     float a = (float)ang; p.cosR[i] = cosf(a); p.sinR[i] = sinf(a);
.LBB0_73:
	s_waitcnt vmcnt(2)
	v_mov_b32_e32 v8, v36
	v_lshl_add_u64 v[38:39], v[2:3], 0, s[18:19]
	v_cmp_ge_u64_e32 vcc, s[36:37], v[38:39]
	s_and_saveexec_b64 s[100:101], vcc
	v_lshl_add_u64 v[38:39], s[16:17], 0, v[38:39]
	v_lshrrev_b64 v[38:39], 5, v[38:39]
	v_and_b32_e32 v38, -4, v38
	v_lshl_add_u64 v[38:39], s[4:5], 0, v[38:39]
	global_load_dword v36, v[38:39], off
	s_mov_b64 exec, s[100:101]
	v_cvt_f64_i32_e32 v[14:15], v8
	v_mul_f64 v[14:15], v[4:5], v[14:15]
	v_mul_f64 v[16:17], v[14:15], s[30:31]
	v_rndne_f64_e32 v[16:17], v[16:17]
	v_fmac_f64_e32 v[14:15], s[34:35], v[16:17]
	v_cvt_f32_f64_e32 v14, v[14:15]
	v_and_b32_e32 v15, 0x7fffffff, v14
	v_lshrrev_b32_e32 v8, 23, v15
	v_and_b32_e32 v16, 0x7fffff, v15
	v_cmp_nlt_f32_e64 s[12:13], |v14|, s40
	v_add_u32_e32 v17, 0xffffff88, v8
	v_or_b32_e32 v16, 0x800000, v16
	s_and_saveexec_b64 s[6:7], s[12:13]
	s_xor_b64 s[38:39], exec, s[6:7]
	s_cbranch_execz .LBB0_75
	v_cmp_lt_u32_e32 vcc, 63, v17
	s_nop 1
	v_cndmask_b32_e32 v8, 0, v12, vcc
	v_add_u32_e32 v8, v8, v17
	v_cmp_lt_u32_e64 s[6:7], 31, v8
	s_nop 1
	v_cndmask_b32_e64 v18, 0, v13, s[6:7]
	v_add_u32_e32 v8, v18, v8
	v_cmp_lt_u32_e64 s[8:9], 31, v8
	s_nop 1
	v_cndmask_b32_e64 v18, 0, v13, s[8:9]
	v_add_u32_e32 v32, v18, v8
	v_mad_u64_u32 v[18:19], s[10:11], v16, s41, 0
	v_mov_b32_e32 v8, v19
	v_mad_u64_u32 v[20:21], s[10:11], v16, s42, v[8:9]
	v_mov_b32_e32 v8, v21
	v_mad_u64_u32 v[22:23], s[10:11], v16, s43, v[8:9]
	v_mov_b32_e32 v8, v23
	v_mad_u64_u32 v[24:25], s[10:11], v16, s44, v[8:9]
	v_mov_b32_e32 v8, v25
	v_mad_u64_u32 v[26:27], s[10:11], v16, s45, v[8:9]
	v_mov_b32_e32 v8, v27
	v_mad_u64_u32 v[28:29], s[10:11], v16, s46, v[8:9]
	v_mov_b32_e32 v8, v29
	v_mad_u64_u32 v[30:31], s[10:11], v16, s47, v[8:9]
	v_cndmask_b32_e32 v19, v28, v24, vcc
	v_cndmask_b32_e32 v8, v30, v26, vcc
	v_cndmask_b32_e32 v23, v31, v28, vcc
	v_cndmask_b32_e64 v21, v8, v19, s[6:7]
	v_cndmask_b32_e64 v8, v23, v8, s[6:7]
	v_cndmask_b32_e32 v23, v26, v22, vcc
	v_cndmask_b32_e64 v19, v19, v23, s[6:7]
	v_cndmask_b32_e32 v20, v24, v20, vcc
	v_cndmask_b32_e64 v8, v8, v21, s[8:9]
	v_cndmask_b32_e64 v21, v21, v19, s[8:9]
	v_sub_u32_e32 v25, 32, v32
	v_cndmask_b32_e64 v23, v23, v20, s[6:7]
	v_alignbit_b32 v26, v8, v21, v25
	v_cmp_eq_u32_e64 s[10:11], 0, v32
	v_cndmask_b32_e64 v19, v19, v23, s[8:9]
	v_cndmask_b32_e32 v18, v22, v18, vcc
	v_cndmask_b32_e64 v8, v26, v8, s[10:11]
	v_alignbit_b32 v24, v21, v19, v25
	v_cndmask_b32_e64 v18, v20, v18, s[6:7]
	v_cndmask_b32_e64 v21, v24, v21, s[10:11]
	v_bfe_u32 v27, v8, 29, 1
	v_cndmask_b32_e64 v18, v23, v18, s[8:9]
	v_alignbit_b32 v24, v8, v21, 30
	v_sub_u32_e32 v28, 0, v27
	v_alignbit_b32 v20, v19, v18, v25
	v_xor_b32_e32 v24, v24, v28
	v_cndmask_b32_e64 v19, v20, v19, s[10:11]
	v_alignbit_b32 v20, v21, v19, 30
	v_ffbh_u32_e32 v21, v24
	v_min_u32_e32 v21, 32, v21
	v_alignbit_b32 v18, v19, v18, 30
	v_xor_b32_e32 v20, v20, v28
	v_sub_u32_e32 v22, 31, v21
	v_xor_b32_e32 v18, v18, v28
	v_alignbit_b32 v23, v24, v20, v22
	v_alignbit_b32 v18, v20, v18, v22
	v_alignbit_b32 v19, v23, v18, 9
	v_ffbh_u32_e32 v20, v19
	v_min_u32_e32 v20, 32, v20
	v_lshrrev_b32_e32 v26, 29, v8
	v_not_b32_e32 v22, v20
	v_alignbit_b32 v18, v19, v18, v22
	v_lshlrev_b32_e32 v19, 31, v26
	v_or_b32_e32 v22, 0x33000000, v19
	v_add_lshl_u32 v20, v20, v21, 23
	v_lshrrev_b32_e32 v18, 9, v18
	v_sub_u32_e32 v20, v22, v20
	v_or_b32_e32 v19, 0.5, v19
	v_lshlrev_b32_e32 v21, 23, v21
	v_or_b32_e32 v18, v20, v18
	v_lshrrev_b32_e32 v20, 9, v23
	v_sub_u32_e32 v19, v19, v21
	v_or_b32_e32 v19, v20, v19
	v_mul_f32_e32 v20, 0x3fc90fda, v19
	v_fma_f32 v21, v19, s49, -v20
	v_fmac_f32_e32 v21, 0x33a22168, v19
	v_fmac_f32_e32 v21, 0x3fc90fda, v18
	v_lshrrev_b32_e32 v8, 30, v8
	v_add_f32_e32 v19, v20, v21
	v_add_u32_e32 v18, v27, v8

; DI f32x16 zero16() { f32x16 z; for (int i = 0; i < 16; ++i) z[i] = 0.f; return z; }
; DI void wait_vm0() { asm volatile("s_waitcnt vmcnt(0)" ::: "memory"); }
; DI void phase_ret(const Params& p, char* lds) {
;     ...
; #pragma unroll 1
;       for (int i = 0; i < 8; ++i) {
;         const int pc = __builtin_amdgcn_readfirstlane(w) * 8 + i; const int row = 2 * pc + (lane >> 5); const int c = (lane & 31) ^ (row & 15);
;         __builtin_amdgcn_global_load_lds((const unsigned*)(p.Kb + (tokb + s0 + row) * D_ + h * 256 + c * 8), (__attribute__((address_space(3))) unsigned*)(k_l + pc * 1024), 16, 0, 0);
;       }
; #pragma unroll
;       for (int i = 0; i < 2; ++i) {
;         int idx = tid + i * NT; int row = idx >> 4, ch = idx & 15;
;         u32x4 v = *(const u32x4*)(p.Vrt + ((size_t)bh * 512 + sl * 64 + row) * S_ + s0 + ch * 8);
;         char* d = v_l + row * 264 + ch * 16; u32x2 a = {v.x, v.y}, bq = {v.z, v.w}; *(u32x2*)d = a; *(u32x2*)(d + 8) = bq;
;       }
;       bf16x8 qf[16];
; #pragma unroll
;       for (int kk = 0; kk < 16; ++kk) qf[kk] = *(const bf16x8*)(p.Q + (tokb + s0 + myi) * D_ + h * 256 + kk * 16 + 8 * hhk);
;       wait_vm0();
;       __syncthreads();
;       f32x16 o = zero16();
;       if (ck > 0) {
;         o = dot16_lds(r_l, et * 32 + l31k, hhk, qf, o);
; #pragma unroll
;         for (int i = 0; i < 16; ++i) o[i] *= qd;
;       }
.LBB0_420:
	v_readfirstlane_b32 s40, v163
	v_xor_b32_e32 v0, v2, v164
	v_lshlrev_b32_e32 v0, 4, v0
	v_lshl_add_u32 v4, s40, 4, v2
	v_ashrrev_i32_e32 v5, 31, v4
	v_lshl_add_u64 v[4:5], s[34:35], 0, v[4:5]
	v_lshlrev_b64 v[4:5], 11, v[4:5]
	s_lshl_b32 s40, s40, 13
	v_lshl_add_u64 v[4:5], s[36:37], 0, v[4:5]
	s_add_i32 m0, s3, s40
	v_lshl_add_u64 v[4:5], v[4:5], 0, v[0:1]
	global_load_lds_dwordx4 v[4:5], off
	s_addk_i32 s3, 0x400
	s_cmpk_eq_i32 s3, 0x2000
	v_add_u32_e32 v2, 2, v2
	s_cbranch_scc0 .LBB0_420
	s_lshl_b64 s[40:41], s[92:93], 1
	v_lshl_add_u64 v[2:3], v[166:167], 0, s[40:41]
	global_load_dwordx4 v[2:5], v[2:3], off
	v_lshl_add_u64 v[250:251], v[168:169], 0, s[40:41]
	global_load_dwordx4 v[246:249], v[250:251], off
	v_lshl_add_u64 v[192:193], s[34:35], 0, v[144:145]
	v_lshlrev_b32_e32 v190, 3, v155
	v_ashrrev_i32_e32 v191, 31, v190
	v_lshlrev_b64 v[250:251], 11, v[192:193]
	v_lshl_add_u64 v[250:251], s[6:7], 0, v[250:251]
	v_lshl_add_u64 v[250:251], v[190:191], 1, v[250:251]
	global_load_dwordx4 v[80:83], v[250:251], off
	global_load_dwordx4 v[84:87], v[250:251], off offset:32
	global_load_dwordx4 v[88:91], v[250:251], off offset:64
	global_load_dwordx4 v[92:95], v[250:251], off offset:96
	global_load_dwordx4 v[96:99], v[250:251], off offset:128
	global_load_dwordx4 v[100:103], v[250:251], off offset:160
	global_load_dwordx4 v[104:107], v[250:251], off offset:192
	global_load_dwordx4 v[108:111], v[250:251], off offset:224
	global_load_dwordx4 v[112:115], v[250:251], off offset:256
	global_load_dwordx4 v[116:119], v[250:251], off offset:288
	global_load_dwordx4 v[120:123], v[250:251], off offset:320
	global_load_dwordx4 v[124:127], v[250:251], off offset:352
	global_load_dwordx4 v[128:131], v[250:251], off offset:384
	global_load_dwordx4 v[132:135], v[250:251], off offset:416
	global_load_dwordx4 v[136:139], v[250:251], off offset:448
	global_load_dwordx4 v[140:143], v[250:251], off offset:480
	v_add_u32_e32 v0, 2, v155
	v_add_u32_e32 v6, 12, v155
	v_add_u32_e32 v7, 14, v155
	v_add_u32_e32 v8, 16, v155
	v_add_u32_e32 v9, 18, v155
	v_add_u32_e32 v10, 20, v155
	v_add_u32_e32 v11, 22, v155
	v_add_u32_e32 v12, 24, v155
	v_add_u32_e32 v13, 26, v155
	v_add_u32_e32 v14, 28, v155
	v_add_u32_e32 v15, 30, v155
	s_cmp_lg_u32 s2, 0
	v_bitop3_b32 v64, v155, v188, 15 bitop3:0x78
	v_bitop3_b32 v65, v0, v188, 15 bitop3:0x78
	v_bitop3_b32 v70, v6, v188, 15 bitop3:0x78
	v_bitop3_b32 v71, v7, v188, 15 bitop3:0x78
	v_bitop3_b32 v72, v8, v188, 15 bitop3:0x78
	v_bitop3_b32 v73, v9, v188, 15 bitop3:0x78
	v_bitop3_b32 v74, v10, v188, 15 bitop3:0x78
	v_bitop3_b32 v75, v11, v188, 15 bitop3:0x78
	v_bitop3_b32 v76, v12, v188, 15 bitop3:0x78
	v_bitop3_b32 v77, v13, v188, 15 bitop3:0x78
	v_bitop3_b32 v78, v14, v188, 15 bitop3:0x78
	v_bitop3_b32 v79, v15, v188, 15 bitop3:0x78
	s_waitcnt vmcnt(17)
	ds_write2_b64 v200, v[2:3], v[4:5] offset1:1
	s_waitcnt vmcnt(16)
	ds_write2_b64 v201, v[246:247], v[248:249] offset1:1
	s_waitcnt vmcnt(0)
	v_add_u32_e32 v2, 4, v155
	v_add_u32_e32 v3, 6, v155
	v_add_u32_e32 v4, 8, v155
	v_add_u32_e32 v5, 10, v155
	v_bitop3_b32 v66, v2, v188, 15 bitop3:0x78
	v_bitop3_b32 v67, v3, v188, 15 bitop3:0x78
	v_bitop3_b32 v68, v4, v188, 15 bitop3:0x78
	v_bitop3_b32 v69, v5, v188, 15 bitop3:0x78
	s_waitcnt lgkmcnt(0)
	s_barrier
	s_cbranch_scc0 .LBB0_423
	v_lshl_add_u32 v0, v188, 9, v197
	v_lshl_add_u32 v2, v64, 4, v0
	ds_read_b128 v[2:5], v2
	v_lshl_add_u32 v6, v65, 4, v0
	ds_read_b128 v[6:9], v6
	v_lshl_add_u32 v10, v68, 4, v0
	v_lshl_add_u32 v11, v69, 4, v0
	v_lshl_add_u32 v14, v70, 4, v0
	v_lshl_add_u32 v15, v71, 4, v0
	s_waitcnt vmcnt(15) lgkmcnt(1)
	v_mfma_f32_32x32x16_bf16 v[48:63], v[2:5], v[80:83], 0
	v_lshl_add_u32 v2, v66, 4, v0
	ds_read_b128 v[2:5], v2
	s_waitcnt vmcnt(14) lgkmcnt(1)
	v_mfma_f32_32x32x16_bf16 v[48:63], v[6:9], v[84:87], v[48:63]
	v_lshl_add_u32 v6, v67, 4, v0
	ds_read_b128 v[6:9], v6
	s_waitcnt vmcnt(13) lgkmcnt(1)
	v_mfma_f32_32x32x16_bf16 v[48:63], v[2:5], v[88:91], v[48:63]
	ds_read_b128 v[2:5], v10
	ds_read_b128 v[10:13], v11
	ds_read_b128 v[204:207], v14
	ds_read_b128 v[208:211], v15
	s_waitcnt vmcnt(12) lgkmcnt(4)
	v_mfma_f32_32x32x16_bf16 v[48:63], v[6:9], v[92:95], v[48:63]
	s_waitcnt vmcnt(11) lgkmcnt(3)
	v_mfma_f32_32x32x16_bf16 v[48:63], v[2:5], v[96:99], v[48:63]
	v_lshl_add_u32 v2, v72, 4, v0
	v_lshl_add_u32 v6, v73, 4, v0
	ds_read_b128 v[2:5], v2
	ds_read_b128 v[6:9], v6
	v_lshl_add_u32 v14, v75, 4, v0
	s_waitcnt vmcnt(10) lgkmcnt(4)
	v_mfma_f32_32x32x16_bf16 v[48:63], v[10:13], v[100:103], v[48:63]
	v_lshl_add_u32 v10, v74, 4, v0
	s_waitcnt vmcnt(9) lgkmcnt(3)
	v_mfma_f32_32x32x16_bf16 v[48:63], v[204:207], v[104:107], v[48:63]
	ds_read_b128 v[10:13], v10
	ds_read_b128 v[204:207], v14
	s_waitcnt vmcnt(8) lgkmcnt(4)
	v_mfma_f32_32x32x16_bf16 v[48:63], v[208:211], v[108:111], v[48:63]
	s_waitcnt vmcnt(7) lgkmcnt(3)
	v_mfma_f32_32x32x16_bf16 v[48:63], v[2:5], v[112:115], v[48:63]
	v_lshl_add_u32 v2, v76, 4, v0
	s_waitcnt vmcnt(6) lgkmcnt(2)
	v_mfma_f32_32x32x16_bf16 v[48:63], v[6:9], v[116:119], v[48:63]
	v_lshl_add_u32 v6, v77, 4, v0
	ds_read_b128 v[2:5], v2
	ds_read_b128 v[6:9], v6
	s_waitcnt vmcnt(5) lgkmcnt(3)
	v_mfma_f32_32x32x16_bf16 v[48:63], v[10:13], v[120:123], v[48:63]
	v_lshl_add_u32 v10, v78, 4, v0
	v_lshl_add_u32 v0, v79, 4, v0
	ds_read_b128 v[10:13], v10
	ds_read_b128 v[208:211], v0
	s_waitcnt vmcnt(4) lgkmcnt(4)
	v_mfma_f32_32x32x16_bf16 v[48:63], v[204:207], v[124:127], v[48:63]
	s_waitcnt vmcnt(3) lgkmcnt(3)
	v_mfma_f32_32x32x16_bf16 v[48:63], v[2:5], v[128:131], v[48:63]
	s_waitcnt vmcnt(2) lgkmcnt(2)
	v_mfma_f32_32x32x16_bf16 v[48:63], v[6:9], v[132:135], v[48:63]
	s_waitcnt vmcnt(1) lgkmcnt(1)
	v_mfma_f32_32x32x16_bf16 v[48:63], v[10:13], v[136:139], v[48:63]
	s_waitcnt vmcnt(0) lgkmcnt(0)
	v_mfma_f32_32x32x16_bf16 v[48:63], v[208:211], v[140:143], v[48:63]
	s_nop 11
	v_pk_mul_f32 v[62:63], v[184:185], v[62:63]
	v_pk_mul_f32 v[60:61], v[182:183], v[60:61]
	v_pk_mul_f32 v[58:59], v[180:181], v[58:59]
	v_pk_mul_f32 v[56:57], v[178:179], v[56:57]
	v_pk_mul_f32 v[54:55], v[176:177], v[54:55]
	v_pk_mul_f32 v[52:53], v[174:175], v[52:53]
	v_pk_mul_f32 v[50:51], v[172:173], v[50:51]
	v_pk_mul_f32 v[48:49], v[158:159], v[48:49]
	v_lshlrev_b32_e32 v10, 2, v155
	v_mul_lo_u32 v0, v188, s90
	s_and_saveexec_b64 s[34:35], vcc
	s_cbranch_execnz .LBB0_424
	s_branch .LBB0_427

; DI unsigned pack2(float lo, float hi) { f32x2 v = {lo, hi}; bf2_t r = __builtin_convertvector(v, bf2_t); return __builtin_bit_cast(unsigned, r); }
; DI f32x16 mfma(bf16x8 a, bf16x8 b, f32x16 c) { return __builtin_amdgcn_mfma_f32_32x32x16_bf16(a, b, c, 0, 0, 0); }
; DI void phase_ret(const Params& p, char* lds) {
;     ...
;       {
;         bf16_t* orow = p.Or + (tokb + s0 + myi) * 2048 + h * 512 + sl * 64 + et * 32;
; #pragma unroll
;         for (int q4 = 0; q4 < 4; ++q4) {
;           u32x2 pk; pk.x = pack2(o[4 * q4], o[4 * q4 + 1]); pk.y = pack2(o[4 * q4 + 2], o[4 * q4 + 3]);
;           *(u32x2*)(orow + 8 * q4 + 4 * hhk) = pk;
;         }
;       }
;       asm volatile("" ::: "memory");
;       if (ck < 15) {
;         const bf16_t* kdr = p.Vt + ((size_t)bh * 256 + w * 32 + l31k) * S_ + s0;
;         bf16x8 ka[8];
; #pragma unroll
;         for (int kk = 0; kk < 8; ++kk) ka[kk] = *(const bf16x8*)(kdr + kk * 16 + 8 * hhk);
; #pragma unroll
;         for (int nt = 0; nt < 2; ++nt) {
; #pragma unroll
;           for (int i = 0; i < 16; ++i) R[nt][i] *= cd;
; #pragma unroll
;           for (int kk = 0; kk < 8; ++kk) {
;             const char* rp = v_l + (nt * 32 + l31k) * 264 + (kk * 16 + 8 * hhk) * 2;
;             s16x4 lo = *(const s16x4*)rp, hi = *(const s16x4*)(rp + 8);
;             bf16x8 bfrag = __builtin_shufflevector(lo, hi, 0, 1, 2, 3, 4, 5, 6, 7);
;             R[nt] = mfma(ka[kk], bfrag, R[nt]);
;           }
;         }
;         __syncthreads();
; #pragma unroll
;         for (int nt = 0; nt < 2; ++nt) {
;           const int e = nt * 32 + l31k;
; #pragma unroll
;           for (int q4 = 0; q4 < 4; ++q4) {
;             int d = w * 32 + 8 * q4 + 4 * hhk;
;             u32x2 pk; pk.x = pack2(R[nt][4 * q4], R[nt][4 * q4 + 1]); pk.y = pack2(R[nt][4 * q4 + 2], R[nt][4 * q4 + 3]);
;             *(u32x2*)(r_l + e * 512 + (((d >> 3) ^ (e & 15)) << 4) + (d & 7) * 2) = pk;
;           }
;         }
.LBB0_427:
	s_or_b64 exec, exec, s[34:35]
	v_lshlrev_b64 v[2:3], 12, v[192:193]
	v_lshl_add_u64 v[2:3], v[170:171], 0, v[2:3]
	v_ashrrev_i32_e32 v11, 31, v10
	v_lshl_add_u64 v[2:3], v[10:11], 1, v[2:3]
	v_cvt_pk_bf16_f32 v4, v48, v49
	v_cvt_pk_bf16_f32 v5, v50, v51
	global_store_dwordx2 v[2:3], v[4:5], off
	v_cvt_pk_bf16_f32 v4, v52, v53
	v_cvt_pk_bf16_f32 v5, v54, v55
	global_store_dwordx2 v[2:3], v[4:5], off offset:16
	v_cvt_pk_bf16_f32 v4, v56, v57
	v_cvt_pk_bf16_f32 v5, v58, v59
	global_store_dwordx2 v[2:3], v[4:5], off offset:32
	v_cvt_pk_bf16_f32 v4, v60, v61
	v_cvt_pk_bf16_f32 v5, v62, v63
	global_store_dwordx2 v[2:3], v[4:5], off offset:48
	s_cmp_lg_u32 s2, 15
	s_cbranch_scc0 .LBB0_418
	v_ashrrev_i32_e32 v189, 31, v188
	v_lshl_add_u64 v[2:3], v[160:161], 0, v[188:189]
	v_lshlrev_b64 v[2:3], 12, v[2:3]
	v_lshl_add_u64 v[2:3], s[82:83], 0, v[2:3]
	v_lshl_add_u64 v[2:3], s[92:93], 1, v[2:3]
	v_lshl_add_u64 v[2:3], v[190:191], 1, v[2:3]
	global_load_dwordx4 v[80:83], v[2:3], off
	global_load_dwordx4 v[84:87], v[2:3], off offset:32
	global_load_dwordx4 v[88:91], v[2:3], off offset:64
	global_load_dwordx4 v[92:95], v[2:3], off offset:96
	global_load_dwordx4 v[96:99], v[2:3], off offset:128
	global_load_dwordx4 v[100:103], v[2:3], off offset:160
	global_load_dwordx4 v[104:107], v[2:3], off offset:192
	global_load_dwordx4 v[108:111], v[2:3], off offset:224
	v_lshlrev_b32_e32 v8, 4, v155
	s_mov_b32 s3, 0x10000
	v_add3_u32 v0, v8, v0, s3
	ds_read2_b64 v[12:15], v0 offset1:1
	v_mov_b32_e32 v157, v156
	v_pk_mul_f32 v[16:17], v[186:187], v[16:17]
	v_pk_mul_f32 v[30:31], v[156:157], v[30:31]
	v_pk_mul_f32 v[28:29], v[156:157], v[28:29]
	v_pk_mul_f32 v[26:27], v[156:157], v[26:27]
	v_pk_mul_f32 v[24:25], v[156:157], v[24:25]
	v_pk_mul_f32 v[22:23], v[156:157], v[22:23]
	v_pk_mul_f32 v[20:21], v[156:157], v[20:21]
	v_pk_mul_f32 v[18:19], v[156:157], v[18:19]
	v_add_u32_e32 v8, 0x2100, v0
	v_pk_mul_f32 v[32:33], v[186:187], v[32:33]
	v_pk_mul_f32 v[46:47], v[156:157], v[46:47]
	v_pk_mul_f32 v[44:45], v[156:157], v[44:45]
	v_pk_mul_f32 v[42:43], v[156:157], v[42:43]
	v_pk_mul_f32 v[40:41], v[156:157], v[40:41]
	v_pk_mul_f32 v[38:39], v[156:157], v[38:39]
	v_pk_mul_f32 v[36:37], v[156:157], v[36:37]
	v_pk_mul_f32 v[34:35], v[156:157], v[34:35]
	v_add_u32_e32 v10, v10, v146
	v_and_b32_e32 v11, 8, v190
	v_lshl_or_b32 v11, v188, 9, v11
	v_lshrrev_b32_e32 v10, 3, v10
	v_add_u32_e32 v11, 0x14200, v11
	v_bitop3_b32 v52, v10, v188, 15 bitop3:0x78
	s_waitcnt vmcnt(7) lgkmcnt(0)
	v_mfma_f32_32x32x16_bf16 v[16:31], v[80:83], v[12:15], v[16:31]
	ds_read2_b64 v[12:15], v8 offset1:1
	v_add_u32_e32 v8, 0x2120, v0
	s_waitcnt lgkmcnt(0)
	v_mfma_f32_32x32x16_bf16 v[32:47], v[80:83], v[12:15], v[32:47]
	ds_read2_b64 v[12:15], v0 offset0:4 offset1:5
	s_waitcnt vmcnt(6) lgkmcnt(0)
	v_mfma_f32_32x32x16_bf16 v[16:31], v[84:87], v[12:15], v[16:31]
	ds_read2_b64 v[12:15], v8 offset1:1
	v_add_u32_e32 v8, 0x2140, v0
	s_waitcnt lgkmcnt(0)
	v_mfma_f32_32x32x16_bf16 v[32:47], v[84:87], v[12:15], v[32:47]
	ds_read2_b64 v[12:15], v0 offset0:8 offset1:9
	s_waitcnt vmcnt(5) lgkmcnt(0)
	v_mfma_f32_32x32x16_bf16 v[16:31], v[88:91], v[12:15], v[16:31]
	ds_read2_b64 v[12:15], v8 offset1:1
	v_add_u32_e32 v8, 0x2160, v0
	s_waitcnt lgkmcnt(0)
	v_mfma_f32_32x32x16_bf16 v[32:47], v[88:91], v[12:15], v[32:47]
	ds_read2_b64 v[12:15], v0 offset0:12 offset1:13
	s_waitcnt vmcnt(4) lgkmcnt(0)
	v_mfma_f32_32x32x16_bf16 v[16:31], v[92:95], v[12:15], v[16:31]
	ds_read2_b64 v[12:15], v8 offset1:1
	v_add_u32_e32 v8, 0x2180, v0
	s_waitcnt lgkmcnt(0)
	v_mfma_f32_32x32x16_bf16 v[32:47], v[92:95], v[12:15], v[32:47]
	ds_read2_b64 v[12:15], v0 offset0:16 offset1:17
	s_waitcnt vmcnt(3) lgkmcnt(0)
	v_mfma_f32_32x32x16_bf16 v[16:31], v[96:99], v[12:15], v[16:31]
	ds_read2_b64 v[12:15], v8 offset1:1
	v_add_u32_e32 v8, 0x21a0, v0
	ds_read2_b64 v[48:51], v8 offset1:1
	s_waitcnt lgkmcnt(1)
	v_mfma_f32_32x32x16_bf16 v[32:47], v[96:99], v[12:15], v[32:47]
	ds_read2_b64 v[12:15], v0 offset0:20 offset1:21
	s_waitcnt vmcnt(2) lgkmcnt(0)
	v_mfma_f32_32x32x16_bf16 v[16:31], v[100:103], v[12:15], v[16:31]
	v_mfma_f32_32x32x16_bf16 v[32:47], v[100:103], v[48:51], v[32:47]
	ds_read2_b64 v[6:9], v0 offset0:24 offset1:25
	s_waitcnt vmcnt(1) lgkmcnt(0)
	v_mfma_f32_32x32x16_bf16 v[16:31], v[104:107], v[6:9], v[16:31]
	v_add_u32_e32 v6, 0x21c0, v0
	ds_read2_b64 v[6:9], v6 offset1:1
	ds_read2_b64 v[48:51], v0 offset0:28 offset1:29
	v_add_u32_e32 v0, 0x21e0, v0
	s_waitcnt lgkmcnt(1)
	v_mfma_f32_32x32x16_bf16 v[32:47], v[104:107], v[6:9], v[32:47]
	ds_read2_b64 v[6:9], v0 offset1:1
	v_add_u32_e32 v12, 1, v10
	v_add_u32_e32 v13, 2, v10
	v_add_u32_e32 v10, 3, v10
	v_lshl_add_u32 v0, v52, 4, v11
	v_bitop3_b32 v12, v12, v188, 15 bitop3:0x78
	v_bitop3_b32 v13, v13, v188, 15 bitop3:0x78
	s_waitcnt vmcnt(0) lgkmcnt(1)
	v_mfma_f32_32x32x16_bf16 v[16:31], v[108:111], v[48:51], v[16:31]
	v_bitop3_b32 v10, v10, v188, 15 bitop3:0x78
	v_lshl_add_u32 v50, v12, 4, v11
	v_lshl_add_u32 v51, v13, 4, v11
	v_lshl_add_u32 v52, v10, 4, v11
	s_waitcnt lgkmcnt(0)
	s_barrier
	v_mfma_f32_32x32x16_bf16 v[32:47], v[108:111], v[6:9], v[32:47]
	s_nop 4
	v_cvt_pk_bf16_f32 v2, v16, v17
	v_cvt_pk_bf16_f32 v3, v18, v19
	v_cvt_pk_bf16_f32 v4, v20, v21
	v_cvt_pk_bf16_f32 v5, v22, v23
	v_cvt_pk_bf16_f32 v6, v24, v25
	v_cvt_pk_bf16_f32 v7, v26, v27
	v_cvt_pk_bf16_f32 v8, v28, v29
	v_cvt_pk_bf16_f32 v9, v30, v31
	v_cvt_pk_bf16_f32 v10, v32, v33
	v_cvt_pk_bf16_f32 v11, v34, v35
	v_cvt_pk_bf16_f32 v12, v36, v37
	v_cvt_pk_bf16_f32 v13, v38, v39
	v_cvt_pk_bf16_f32 v14, v40, v41
	v_cvt_pk_bf16_f32 v15, v42, v43
	v_cvt_pk_bf16_f32 v48, v44, v45
	v_cvt_pk_bf16_f32 v49, v46, v47
	ds_write_b64 v0, v[2:3]
	ds_write_b64 v50, v[4:5]
	ds_write_b64 v51, v[6:7]
	ds_write_b64 v52, v[8:9]
	ds_write_b64 v0, v[10:11] offset:16384
	ds_write_b64 v50, v[12:13] offset:16384
	ds_write_b64 v51, v[14:15] offset:16384
	ds_write_b64 v52, v[48:49] offset:16384
	s_branch .LBB0_418

; DI int crow(int i, int hh) { return (i & 3) + 8 * (i >> 2) + 4 * hh; }
; DI float xhalf_sum(float v) { auto r = __builtin_amdgcn_permlane32_swap(__float_as_uint(v), __float_as_uint(v), false, false); return __uint_as_float(r[0]) + __uint_as_float(r[1]); }
; DI void phase_da_attn(const Params& p, int j, char* lds) {
;     ...
;     if (c == 0) {
;       float ss = 0.f;
; #pragma unroll
;       for (int et = 0; et < 4; ++et)
; #pragma unroll
;         for (int i = 0; i < 16; ++i) { float v = o[et][i] * inv - lam * cmb[(qg * 128 + et * 32 + crow(i, hh)) * 32 + l31]; o[et][i] = v; ss += v * v; }
;       ss = xhalf_sum(ss);
;       const float r = rsqrtf(ss * (1.f / 128.f) + LN_EPS) * (1.f - li);
.LBB0_509:
	s_or_b64 exec, exec, s[6:7]
	s_waitcnt lgkmcnt(0)
	s_barrier
	s_and_saveexec_b64 s[6:7], s[40:41]
	s_cbranch_execz .LBB0_485
	ds_read2_b32 v[96:97], v186 offset1:32
	ds_read2_b32 v[98:99], v186 offset0:64 offset1:96
	ds_read2_b32 v[100:101], v81 offset1:32
	ds_read2_b32 v[102:103], v81 offset0:64 offset1:96
	ds_read2_b32 v[104:105], v80 offset1:32
	ds_read2_b32 v[106:107], v80 offset0:64 offset1:96
	ds_read2_b32 v[108:109], v79 offset1:32
	ds_read2_b32 v[110:111], v79 offset0:64 offset1:96
	ds_read2_b32 v[112:113], v78 offset1:32
	s_waitcnt vmcnt(2)
	ds_read2_b32 v[114:115], v78 offset0:64 offset1:96
	ds_read2_b32 v[116:117], v77 offset1:32
	ds_read2_b32 v[118:119], v77 offset0:64 offset1:96
	ds_read2_b32 v[120:121], v76 offset1:32
	s_waitcnt vmcnt(1)
	ds_read2_b32 v[122:123], v76 offset0:64 offset1:96
	ds_read2_b32 v[124:125], v75 offset1:32
	s_waitcnt vmcnt(0)
	ds_read2_b32 v[126:127], v75 offset0:64 offset1:96
	ds_read2_b32 v[128:129], v74 offset1:32
	ds_read2_b32 v[154:155], v74 offset0:64 offset1:96
	ds_read2_b32 v[156:157], v73 offset1:32
	ds_read2_b32 v[158:159], v73 offset0:64 offset1:96
	ds_read2_b32 v[160:161], v72 offset1:32
	ds_read2_b32 v[166:167], v72 offset0:64 offset1:96
	ds_read2_b32 v[92:93], v71 offset1:32
	ds_read2_b32 v[94:95], v71 offset0:64 offset1:96
	ds_read2_b32 v[88:89], v69 offset1:32
	ds_read2_b32 v[90:91], v69 offset0:64 offset1:96
	ds_read2_b32 v[84:85], v68 offset1:32
	ds_read2_b32 v[86:87], v68 offset0:64 offset1:96
	ds_read2_b32 v[80:81], v67 offset1:32
	ds_read2_b32 v[82:83], v67 offset0:64 offset1:96
	ds_read2_b32 v[74:75], v66 offset1:32
	ds_read2_b32 v[78:79], v66 offset0:64 offset1:96
	s_waitcnt lgkmcnt(14)
	v_pk_mul_f32 v[76:77], v[130:131], v[98:99]
	v_lshl_add_u64 v[66:67], s[84:85], 0, v[152:153]
	v_pk_fma_f32 v[52:53], v[52:53], v[70:71], v[76:77] op_sel_hi:[1,0,1] neg_lo:[0,0,1] neg_hi:[0,0,1]
	v_pk_mul_f32 v[76:77], v[130:131], v[96:97]
	v_mul_f32_e32 v96, v53, v53
	v_pk_fma_f32 v[50:51], v[50:51], v[70:71], v[76:77] op_sel_hi:[1,0,1] neg_lo:[0,0,1] neg_hi:[0,0,1]
	s_lshl_b32 s92, s35, 1
	v_mul_f32_e32 v76, v51, v51
	v_pk_fma_f32 v[76:77], v[50:51], v[50:51], v[76:77] op_sel_hi:[1,1,0]
	v_lshl_add_u64 v[72:73], v[66:67], 0, s[92:93]
	v_pk_fma_f32 v[76:77], v[52:53], v[52:53], v[76:77]
	global_load_dwordx4 v[66:69], v[144:145], off
	v_pk_add_f32 v[96:97], v[76:77], v[96:97] op_sel_hi:[1,0]
	v_pk_mul_f32 v[76:77], v[130:131], v[102:103]
	s_waitcnt lgkmcnt(7)
	v_pk_mul_f32 v[88:89], v[130:131], v[88:89]
	v_pk_fma_f32 v[56:57], v[56:57], v[70:71], v[76:77] op_sel_hi:[1,0,1] neg_lo:[0,0,1] neg_hi:[0,0,1]
	v_pk_mul_f32 v[76:77], v[130:131], v[100:101]
	v_pk_fma_f32 v[2:3], v[2:3], v[70:71], v[88:89] op_sel_hi:[1,0,1] neg_lo:[0,0,1] neg_hi:[0,0,1]
	v_pk_fma_f32 v[76:77], v[54:55], v[70:71], v[76:77] op_sel_hi:[1,0,1] neg_lo:[0,0,1] neg_hi:[0,0,1]
	s_waitcnt lgkmcnt(6)
	v_pk_mul_f32 v[90:91], v[130:131], v[90:91]
	v_pk_fma_f32 v[54:55], v[76:77], v[76:77], v[96:97]
	v_mul_f32_e32 v96, v77, v77
	v_pk_add_f32 v[54:55], v[54:55], v[96:97] op_sel_hi:[1,0]
	v_mul_f32_e32 v96, v57, v57
	v_pk_fma_f32 v[54:55], v[56:57], v[56:57], v[54:55]
	v_mul_f32_e32 v88, v3, v3
	v_pk_add_f32 v[96:97], v[54:55], v[96:97] op_sel_hi:[1,0]
	v_pk_mul_f32 v[54:55], v[130:131], v[106:107]
	v_pk_fma_f32 v[4:5], v[4:5], v[70:71], v[90:91] op_sel_hi:[1,0,1] neg_lo:[0,0,1] neg_hi:[0,0,1]
	v_pk_fma_f32 v[54:55], v[60:61], v[70:71], v[54:55] op_sel_hi:[1,0,1] neg_lo:[0,0,1] neg_hi:[0,0,1]
	v_pk_mul_f32 v[60:61], v[130:131], v[104:105]
	s_waitcnt lgkmcnt(4)
	v_pk_mul_f32 v[86:87], v[130:131], v[86:87]
	v_pk_fma_f32 v[60:61], v[58:59], v[70:71], v[60:61] op_sel_hi:[1,0,1] neg_lo:[0,0,1] neg_hi:[0,0,1]
	v_pk_fma_f32 v[86:87], v[8:9], v[70:71], v[86:87] op_sel_hi:[1,0,1] neg_lo:[0,0,1] neg_hi:[0,0,1]
	v_pk_fma_f32 v[58:59], v[60:61], v[60:61], v[96:97]
	v_mul_f32_e32 v96, v61, v61
	v_pk_add_f32 v[58:59], v[58:59], v[96:97] op_sel_hi:[1,0]
	v_mul_f32_e32 v96, v55, v55
	v_pk_fma_f32 v[58:59], v[54:55], v[54:55], v[58:59]
	v_pk_mul_f32 v[8:9], v[130:131], v[84:85]
	v_pk_add_f32 v[96:97], v[58:59], v[96:97] op_sel_hi:[1,0]
	v_pk_mul_f32 v[58:59], v[130:131], v[110:111]
	v_pk_fma_f32 v[84:85], v[6:7], v[70:71], v[8:9] op_sel_hi:[1,0,1] neg_lo:[0,0,1] neg_hi:[0,0,1]
	v_pk_fma_f32 v[58:59], v[64:65], v[70:71], v[58:59] op_sel_hi:[1,0,1] neg_lo:[0,0,1] neg_hi:[0,0,1]
	v_pk_mul_f32 v[64:65], v[130:131], v[108:109]
	v_mul_f32_e32 v8, v85, v85
	v_pk_fma_f32 v[62:63], v[62:63], v[70:71], v[64:65] op_sel_hi:[1,0,1] neg_lo:[0,0,1] neg_hi:[0,0,1]
	s_mov_b32 s2, 0x800000
	v_pk_fma_f32 v[64:65], v[62:63], v[62:63], v[96:97]
	v_mul_f32_e32 v96, v63, v63
	v_pk_add_f32 v[64:65], v[64:65], v[96:97] op_sel_hi:[1,0]
	v_mul_f32_e32 v96, v59, v59
	v_pk_fma_f32 v[64:65], v[58:59], v[58:59], v[64:65]
	s_nop 0
	v_pk_add_f32 v[96:97], v[64:65], v[96:97] op_sel_hi:[1,0]
	v_pk_mul_f32 v[64:65], v[130:131], v[114:115]
	s_nop 0
	v_pk_fma_f32 v[36:37], v[36:37], v[70:71], v[64:65] op_sel_hi:[1,0,1] neg_lo:[0,0,1] neg_hi:[0,0,1]
	v_pk_mul_f32 v[64:65], v[130:131], v[112:113]
	s_nop 0
	v_pk_fma_f32 v[64:65], v[34:35], v[70:71], v[64:65] op_sel_hi:[1,0,1] neg_lo:[0,0,1] neg_hi:[0,0,1]
	s_nop 0
	v_pk_fma_f32 v[34:35], v[64:65], v[64:65], v[96:97]
	v_mul_f32_e32 v96, v65, v65
	v_pk_add_f32 v[34:35], v[34:35], v[96:97] op_sel_hi:[1,0]
	v_mul_f32_e32 v96, v37, v37
	v_pk_fma_f32 v[34:35], v[36:37], v[36:37], v[34:35]
	s_nop 0
	v_pk_add_f32 v[96:97], v[34:35], v[96:97] op_sel_hi:[1,0]
	v_pk_mul_f32 v[34:35], v[130:131], v[118:119]
	s_nop 0
	v_pk_fma_f32 v[34:35], v[40:41], v[70:71], v[34:35] op_sel_hi:[1,0,1] neg_lo:[0,0,1] neg_hi:[0,0,1]
	v_pk_mul_f32 v[40:41], v[130:131], v[116:117]
; DI int crow(int i, int hh) { return (i & 3) + 8 * (i >> 2) + 4 * hh; }
; DI float xhalf_sum(float v) { auto r = __builtin_amdgcn_permlane32_swap(__float_as_uint(v), __float_as_uint(v), false, false); return __uint_as_float(r[0]) + __uint_as_float(r[1]); }
; DI void phase_da_attn(const Params& p, int j, char* lds) {
;     ...
;       float ss = 0.f;
; #pragma unroll
;       for (int et = 0; et < 4; ++et)
; #pragma unroll
;         for (int i = 0; i < 16; ++i) { float v = o[et][i] * inv - lam * cmb[(qg * 128 + et * 32 + crow(i, hh)) * 32 + l31]; o[et][i] = v; ss += v * v; }
;       ss = xhalf_sum(ss);
	s_nop 0
	v_pk_fma_f32 v[40:41], v[38:39], v[70:71], v[40:41] op_sel_hi:[1,0,1] neg_lo:[0,0,1] neg_hi:[0,0,1]
	s_nop 0
	v_pk_fma_f32 v[38:39], v[40:41], v[40:41], v[96:97]
	v_mul_f32_e32 v96, v41, v41
	v_pk_add_f32 v[38:39], v[38:39], v[96:97] op_sel_hi:[1,0]
	v_mul_f32_e32 v96, v35, v35
	v_pk_fma_f32 v[38:39], v[34:35], v[34:35], v[38:39]
	s_nop 0
	v_pk_add_f32 v[96:97], v[38:39], v[96:97] op_sel_hi:[1,0]
	v_pk_mul_f32 v[38:39], v[130:131], v[122:123]
	s_nop 0
	v_pk_fma_f32 v[38:39], v[44:45], v[70:71], v[38:39] op_sel_hi:[1,0,1] neg_lo:[0,0,1] neg_hi:[0,0,1]
	v_pk_mul_f32 v[44:45], v[130:131], v[120:121]
	s_nop 0
	v_pk_fma_f32 v[44:45], v[42:43], v[70:71], v[44:45] op_sel_hi:[1,0,1] neg_lo:[0,0,1] neg_hi:[0,0,1]
	s_nop 0
	v_pk_fma_f32 v[42:43], v[44:45], v[44:45], v[96:97]
	v_mul_f32_e32 v96, v45, v45
	v_pk_add_f32 v[42:43], v[42:43], v[96:97] op_sel_hi:[1,0]
	v_mul_f32_e32 v96, v39, v39
	v_pk_fma_f32 v[42:43], v[38:39], v[38:39], v[42:43]
	s_nop 0
	v_pk_add_f32 v[96:97], v[42:43], v[96:97] op_sel_hi:[1,0]
	v_pk_mul_f32 v[42:43], v[130:131], v[126:127]
	s_nop 0
	v_pk_fma_f32 v[42:43], v[48:49], v[70:71], v[42:43] op_sel_hi:[1,0,1] neg_lo:[0,0,1] neg_hi:[0,0,1]
	v_pk_mul_f32 v[48:49], v[130:131], v[124:125]
	s_nop 0
	v_pk_fma_f32 v[46:47], v[46:47], v[70:71], v[48:49] op_sel_hi:[1,0,1] neg_lo:[0,0,1] neg_hi:[0,0,1]
	s_nop 0
	v_pk_fma_f32 v[48:49], v[46:47], v[46:47], v[96:97]
	v_mul_f32_e32 v96, v47, v47
	v_pk_add_f32 v[48:49], v[48:49], v[96:97] op_sel_hi:[1,0]
	v_mul_f32_e32 v96, v43, v43
	v_pk_fma_f32 v[48:49], v[42:43], v[42:43], v[48:49]
	s_nop 0
	v_pk_add_f32 v[96:97], v[48:49], v[96:97] op_sel_hi:[1,0]
	v_pk_mul_f32 v[48:49], v[130:131], v[154:155]
	s_nop 0
	v_pk_fma_f32 v[20:21], v[20:21], v[70:71], v[48:49] op_sel_hi:[1,0,1] neg_lo:[0,0,1] neg_hi:[0,0,1]
	v_pk_mul_f32 v[48:49], v[130:131], v[128:129]
	s_nop 0
	v_pk_fma_f32 v[48:49], v[18:19], v[70:71], v[48:49] op_sel_hi:[1,0,1] neg_lo:[0,0,1] neg_hi:[0,0,1]
	s_nop 0
	v_pk_fma_f32 v[18:19], v[48:49], v[48:49], v[96:97]
	v_mul_f32_e32 v96, v49, v49
	v_pk_add_f32 v[18:19], v[18:19], v[96:97] op_sel_hi:[1,0]
	v_mul_f32_e32 v96, v21, v21
	v_pk_fma_f32 v[18:19], v[20:21], v[20:21], v[18:19]
	s_nop 0
	v_pk_add_f32 v[96:97], v[18:19], v[96:97] op_sel_hi:[1,0]
	v_pk_mul_f32 v[18:19], v[130:131], v[158:159]
	s_nop 0
	v_pk_fma_f32 v[18:19], v[24:25], v[70:71], v[18:19] op_sel_hi:[1,0,1] neg_lo:[0,0,1] neg_hi:[0,0,1]
	v_pk_mul_f32 v[24:25], v[130:131], v[156:157]
	s_nop 0
	v_pk_fma_f32 v[24:25], v[22:23], v[70:71], v[24:25] op_sel_hi:[1,0,1] neg_lo:[0,0,1] neg_hi:[0,0,1]
	s_nop 0
	v_pk_fma_f32 v[22:23], v[24:25], v[24:25], v[96:97]
	v_mul_f32_e32 v96, v25, v25
	v_pk_add_f32 v[22:23], v[22:23], v[96:97] op_sel_hi:[1,0]
	v_mul_f32_e32 v96, v19, v19
	v_pk_fma_f32 v[22:23], v[18:19], v[18:19], v[22:23]
	s_nop 0
	v_pk_add_f32 v[96:97], v[22:23], v[96:97] op_sel_hi:[1,0]
	v_pk_mul_f32 v[22:23], v[130:131], v[166:167]
	s_nop 0
	v_pk_fma_f32 v[22:23], v[28:29], v[70:71], v[22:23] op_sel_hi:[1,0,1] neg_lo:[0,0,1] neg_hi:[0,0,1]
	v_pk_mul_f32 v[28:29], v[130:131], v[160:161]
	s_nop 0
	v_pk_fma_f32 v[28:29], v[26:27], v[70:71], v[28:29] op_sel_hi:[1,0,1] neg_lo:[0,0,1] neg_hi:[0,0,1]
	s_nop 0
	v_pk_fma_f32 v[26:27], v[28:29], v[28:29], v[96:97]
	v_mul_f32_e32 v96, v29, v29
	v_pk_add_f32 v[26:27], v[26:27], v[96:97] op_sel_hi:[1,0]
	v_mul_f32_e32 v96, v23, v23
	v_pk_fma_f32 v[26:27], v[22:23], v[22:23], v[26:27]
	s_nop 0
	v_pk_add_f32 v[96:97], v[26:27], v[96:97] op_sel_hi:[1,0]
	v_pk_mul_f32 v[26:27], v[130:131], v[94:95]
	s_nop 0
	v_pk_fma_f32 v[26:27], v[32:33], v[70:71], v[26:27] op_sel_hi:[1,0,1] neg_lo:[0,0,1] neg_hi:[0,0,1]
	v_pk_mul_f32 v[32:33], v[130:131], v[92:93]
	s_nop 0
	v_pk_fma_f32 v[30:31], v[30:31], v[70:71], v[32:33] op_sel_hi:[1,0,1] neg_lo:[0,0,1] neg_hi:[0,0,1]
	s_nop 0
	v_pk_fma_f32 v[32:33], v[30:31], v[30:31], v[96:97]
	v_mul_f32_e32 v92, v31, v31
	v_pk_add_f32 v[32:33], v[32:33], v[92:93] op_sel_hi:[1,0]
	v_mul_f32_e32 v92, v27, v27
	v_pk_fma_f32 v[32:33], v[26:27], v[26:27], v[32:33]
	s_nop 0
	v_pk_add_f32 v[32:33], v[32:33], v[92:93] op_sel_hi:[1,0]
	s_nop 0
	v_pk_fma_f32 v[32:33], v[2:3], v[2:3], v[32:33]
	s_nop 0
	v_pk_add_f32 v[32:33], v[32:33], v[88:89] op_sel_hi:[1,0]
	v_mul_f32_e32 v88, v5, v5
	v_pk_fma_f32 v[32:33], v[4:5], v[4:5], v[32:33]
	s_nop 0
	v_pk_add_f32 v[32:33], v[32:33], v[88:89] op_sel_hi:[1,0]
	s_nop 0
	v_pk_fma_f32 v[6:7], v[84:85], v[84:85], v[32:33]
	s_nop 0
	v_pk_add_f32 v[6:7], v[6:7], v[8:9] op_sel_hi:[1,0]
	v_mul_f32_e32 v8, v87, v87
	v_pk_fma_f32 v[6:7], v[86:87], v[86:87], v[6:7]
	s_nop 0
	v_pk_add_f32 v[6:7], v[6:7], v[8:9] op_sel_hi:[1,0]
	s_waitcnt lgkmcnt(2)
	v_pk_mul_f32 v[8:9], v[130:131], v[82:83]
	s_nop 0
	v_pk_fma_f32 v[12:13], v[12:13], v[70:71], v[8:9] op_sel_hi:[1,0,1] neg_lo:[0,0,1] neg_hi:[0,0,1]
	v_pk_mul_f32 v[8:9], v[130:131], v[80:81]
	s_nop 0
	v_pk_fma_f32 v[10:11], v[10:11], v[70:71], v[8:9] op_sel_hi:[1,0,1] neg_lo:[0,0,1] neg_hi:[0,0,1]
	s_nop 0
	v_pk_fma_f32 v[6:7], v[10:11], v[10:11], v[6:7]
	v_mul_f32_e32 v8, v11, v11
	v_pk_add_f32 v[6:7], v[6:7], v[8:9] op_sel_hi:[1,0]
	v_mul_f32_e32 v8, v13, v13
	v_pk_fma_f32 v[6:7], v[12:13], v[12:13], v[6:7]
	s_nop 0
	v_pk_add_f32 v[6:7], v[6:7], v[8:9] op_sel_hi:[1,0]
	s_waitcnt lgkmcnt(0)
; DI unsigned pack2(float lo, float hi) { f32x2 v = {lo, hi}; bf2_t r = __builtin_convertvector(v, bf2_t); return __builtin_bit_cast(unsigned, r); }
; DI float xhalf_sum(float v) { auto r = __builtin_amdgcn_permlane32_swap(__float_as_uint(v), __float_as_uint(v), false, false); return __uint_as_float(r[0]) + __uint_as_float(r[1]); }
; DI void phase_da_attn(const Params& p, int j, char* lds) {
;     ...
;       ss = xhalf_sum(ss);
;       const float r = rsqrtf(ss * (1.f / 128.f) + LN_EPS) * (1.f - li);
;       bf16_t* orow = p.Oa + (tokb + myq) * D_ + h * 128;
;       const float* sg = p.subln_g + j * 128;
; #pragma unroll
;       for (int et = 0; et < 4; ++et)
; #pragma unroll
;         for (int qd = 0; qd < 4; ++qd) {
;           int e = et * 32 + 8 * qd + 4 * hh;
;           f32x4 gv = *(const f32x4*)(sg + e);
;           u32x2 pk; pk.x = pack2(o[et][4 * qd] * r * gv[0], o[et][4 * qd + 1] * r * gv[1]); pk.y = pack2(o[et][4 * qd + 2] * r * gv[2], o[et][4 * qd + 3] * r * gv[3]);
;           *(u32x2*)(orow + e) = pk;
;         }
	v_pk_mul_f32 v[8:9], v[130:131], v[78:79]
	s_nop 0
	v_pk_fma_f32 v[16:17], v[16:17], v[70:71], v[8:9] op_sel_hi:[1,0,1] neg_lo:[0,0,1] neg_hi:[0,0,1]
	v_pk_mul_f32 v[8:9], v[130:131], v[74:75]
	s_nop 0
	v_pk_fma_f32 v[14:15], v[14:15], v[70:71], v[8:9] op_sel_hi:[1,0,1] neg_lo:[0,0,1] neg_hi:[0,0,1]
	s_nop 0
	v_pk_fma_f32 v[6:7], v[14:15], v[14:15], v[6:7]
	v_mul_f32_e32 v8, v15, v15
	v_pk_add_f32 v[6:7], v[6:7], v[8:9] op_sel_hi:[1,0]
	v_mul_f32_e32 v8, v17, v17
	v_pk_fma_f32 v[6:7], v[16:17], v[16:17], v[6:7]
	s_nop 0
	v_pk_add_f32 v[6:7], v[6:7], v[8:9] op_sel_hi:[1,0]
	s_nop 0
	v_mov_b32_e32 v7, v6
	s_nop 1
	v_permlane32_swap_b32_e32 v6, v7
	v_add_f32_e32 v6, v6, v7
	v_fmamk_f32 v6, v6, 0x3c000000, v218
	v_mul_f32_e32 v7, 0x4b800000, v6
	v_cmp_gt_f32_e32 vcc, s2, v6
	s_nop 1
	v_cndmask_b32_e32 v6, v6, v7, vcc
	v_rsq_f32_e32 v8, v6
	v_lshlrev_b32_e32 v6, 1, v142
	v_mov_b32_e32 v7, v1
	v_lshl_add_u64 v[32:33], v[72:73], 0, v[6:7]
	v_mul_f32_e32 v6, 0x45800000, v8
	v_cndmask_b32_e32 v6, v8, v6, vcc
	v_mul_f32_e32 v70, v181, v6
	v_pk_mul_f32 v[6:7], v[50:51], v[70:71] op_sel_hi:[1,0]
	v_pk_mul_f32 v[8:9], v[52:53], v[70:71] op_sel_hi:[1,0]
	s_waitcnt vmcnt(0)
	v_pk_mul_f32 v[6:7], v[66:67], v[6:7]
	v_pk_mul_f32 v[8:9], v[68:69], v[8:9]
	v_cvt_pk_bf16_f32 v6, v6, v7
	v_cvt_pk_bf16_f32 v7, v8, v9
	global_store_dwordx2 v[32:33], v[6:7], off
	global_load_dwordx4 v[226:229], v[144:145], off offset:32
	global_load_dwordx4 v[230:233], v[144:145], off offset:64
	global_load_dwordx4 v[234:237], v[144:145], off offset:96
	global_load_dwordx4 v[238:241], v[144:145], off offset:128
	global_load_dwordx4 v[242:245], v[144:145], off offset:160
	global_load_dwordx4 v[246:249], v[144:145], off offset:192
	v_pk_mul_f32 v[50:51], v[76:77], v[70:71] op_sel_hi:[1,0]
	v_pk_mul_f32 v[52:53], v[54:55], v[70:71] op_sel_hi:[1,0]
	v_pk_mul_f32 v[36:37], v[36:37], v[70:71] op_sel_hi:[1,0]
	v_pk_mul_f32 v[34:35], v[34:35], v[70:71] op_sel_hi:[1,0]
	v_pk_mul_f32 v[20:21], v[20:21], v[70:71] op_sel_hi:[1,0]
	v_pk_mul_f32 v[18:19], v[18:19], v[70:71] op_sel_hi:[1,0]
	v_pk_mul_f32 v[2:3], v[2:3], v[70:71] op_sel_hi:[1,0]
	v_pk_mul_f32 v[4:5], v[4:5], v[70:71] op_sel_hi:[1,0]
	s_waitcnt vmcnt(0)
	v_mov_b32_e32 v6, v226
	v_mov_b32_e32 v7, v227
	v_mov_b32_e32 v8, v228
	v_mov_b32_e32 v9, v229
	v_pk_mul_f32 v[6:7], v[6:7], v[50:51]
	v_pk_mul_f32 v[50:51], v[56:57], v[70:71] op_sel_hi:[1,0]
	v_cvt_pk_bf16_f32 v6, v6, v7
	v_pk_mul_f32 v[8:9], v[8:9], v[50:51]
	v_pk_mul_f32 v[50:51], v[60:61], v[70:71] op_sel_hi:[1,0]
	v_cvt_pk_bf16_f32 v7, v8, v9
	global_store_dwordx2 v[32:33], v[6:7], off offset:16
	v_mov_b32_e32 v6, v230
	v_mov_b32_e32 v7, v231
	v_mov_b32_e32 v8, v232
	v_mov_b32_e32 v9, v233
	v_pk_mul_f32 v[6:7], v[6:7], v[50:51]
	v_pk_mul_f32 v[8:9], v[8:9], v[52:53]
	v_cvt_pk_bf16_f32 v6, v6, v7
	v_cvt_pk_bf16_f32 v7, v8, v9
	global_store_dwordx2 v[32:33], v[6:7], off offset:32
	v_pk_mul_f32 v[50:51], v[62:63], v[70:71] op_sel_hi:[1,0]
	v_pk_mul_f32 v[52:53], v[58:59], v[70:71] op_sel_hi:[1,0]
	v_mov_b32_e32 v6, v234
	v_mov_b32_e32 v7, v235
	v_mov_b32_e32 v8, v236
	v_mov_b32_e32 v9, v237
	v_pk_mul_f32 v[6:7], v[6:7], v[50:51]
	v_pk_mul_f32 v[8:9], v[8:9], v[52:53]
	v_cvt_pk_bf16_f32 v6, v6, v7
	v_cvt_pk_bf16_f32 v7, v8, v9
	global_store_dwordx2 v[32:33], v[6:7], off offset:48
	v_pk_mul_f32 v[50:51], v[64:65], v[70:71] op_sel_hi:[1,0]
	v_mov_b32_e32 v6, v238
	v_mov_b32_e32 v7, v239
	v_mov_b32_e32 v8, v240
	v_mov_b32_e32 v9, v241
	v_pk_mul_f32 v[8:9], v[8:9], v[36:37]
	v_pk_mul_f32 v[6:7], v[6:7], v[50:51]
	v_pk_mul_f32 v[36:37], v[40:41], v[70:71] op_sel_hi:[1,0]
	v_cvt_pk_bf16_f32 v6, v6, v7
	v_cvt_pk_bf16_f32 v7, v8, v9
	global_store_dwordx2 v[32:33], v[6:7], off offset:64
	v_mov_b32_e32 v6, v242
	v_mov_b32_e32 v7, v243
	v_mov_b32_e32 v8, v244
	v_mov_b32_e32 v9, v245
	v_pk_mul_f32 v[6:7], v[36:37], v[6:7]
	v_pk_mul_f32 v[8:9], v[34:35], v[8:9]
	v_cvt_pk_bf16_f32 v6, v6, v7
	v_cvt_pk_bf16_f32 v7, v8, v9
	global_store_dwordx2 v[32:33], v[6:7], off offset:80
	v_pk_mul_f32 v[34:35], v[44:45], v[70:71] op_sel_hi:[1,0]
	v_pk_mul_f32 v[36:37], v[38:39], v[70:71] op_sel_hi:[1,0]
	v_mov_b32_e32 v6, v246
	v_mov_b32_e32 v7, v247
	v_mov_b32_e32 v8, v248
	v_mov_b32_e32 v9, v249
	v_pk_mul_f32 v[6:7], v[34:35], v[6:7]
	v_pk_mul_f32 v[8:9], v[36:37], v[8:9]
	v_cvt_pk_bf16_f32 v6, v6, v7
	v_cvt_pk_bf16_f32 v7, v8, v9
	global_store_dwordx2 v[32:33], v[6:7], off offset:96
	global_load_dwordx4 v[226:229], v[144:145], off offset:224
	global_load_dwordx4 v[230:233], v[144:145], off offset:256
	global_load_dwordx4 v[234:237], v[144:145], off offset:288
	global_load_dwordx4 v[238:241], v[144:145], off offset:320
	global_load_dwordx4 v[242:245], v[144:145], off offset:352
	global_load_dwordx4 v[246:249], v[144:145], off offset:384
	v_pk_mul_f32 v[34:35], v[46:47], v[70:71] op_sel_hi:[1,0]
	v_pk_mul_f32 v[36:37], v[42:43], v[70:71] op_sel_hi:[1,0]
	s_waitcnt vmcnt(0)
; DI unsigned pack2(float lo, float hi) { f32x2 v = {lo, hi}; bf2_t r = __builtin_convertvector(v, bf2_t); return __builtin_bit_cast(unsigned, r); }
; DI void phase_da_attn(const Params& p, int j, char* lds) {
;     ...
; #pragma unroll
;       for (int et = 0; et < 4; ++et)
; #pragma unroll
;         for (int qd = 0; qd < 4; ++qd) {
;           int e = et * 32 + 8 * qd + 4 * hh;
;           f32x4 gv = *(const f32x4*)(sg + e);
;           u32x2 pk; pk.x = pack2(o[et][4 * qd] * r * gv[0], o[et][4 * qd + 1] * r * gv[1]); pk.y = pack2(o[et][4 * qd + 2] * r * gv[2], o[et][4 * qd + 3] * r * gv[3]);
;           *(u32x2*)(orow + e) = pk;
;         }
	v_mov_b32_e32 v6, v226
	v_mov_b32_e32 v7, v227
	v_mov_b32_e32 v8, v228
	v_mov_b32_e32 v9, v229
	v_pk_mul_f32 v[6:7], v[34:35], v[6:7]
	v_pk_mul_f32 v[8:9], v[36:37], v[8:9]
	v_cvt_pk_bf16_f32 v6, v6, v7
	v_cvt_pk_bf16_f32 v7, v8, v9
	global_store_dwordx2 v[32:33], v[6:7], off offset:112
	v_pk_mul_f32 v[34:35], v[48:49], v[70:71] op_sel_hi:[1,0]
	v_mov_b32_e32 v6, v230
	v_mov_b32_e32 v7, v231
	v_mov_b32_e32 v8, v232
	v_mov_b32_e32 v9, v233
	v_pk_mul_f32 v[8:9], v[20:21], v[8:9]
	v_pk_mul_f32 v[6:7], v[34:35], v[6:7]
	v_pk_mul_f32 v[20:21], v[24:25], v[70:71] op_sel_hi:[1,0]
	v_cvt_pk_bf16_f32 v6, v6, v7
	v_cvt_pk_bf16_f32 v7, v8, v9
	global_store_dwordx2 v[32:33], v[6:7], off offset:128
	v_mov_b32_e32 v6, v234
	v_mov_b32_e32 v7, v235
	v_mov_b32_e32 v8, v236
	v_mov_b32_e32 v9, v237
	v_pk_mul_f32 v[6:7], v[20:21], v[6:7]
	v_pk_mul_f32 v[8:9], v[18:19], v[8:9]
	v_cvt_pk_bf16_f32 v6, v6, v7
	v_cvt_pk_bf16_f32 v7, v8, v9
	global_store_dwordx2 v[32:33], v[6:7], off offset:144
	v_pk_mul_f32 v[18:19], v[28:29], v[70:71] op_sel_hi:[1,0]
	v_pk_mul_f32 v[20:21], v[22:23], v[70:71] op_sel_hi:[1,0]
	v_mov_b32_e32 v6, v238
	v_mov_b32_e32 v7, v239
	v_mov_b32_e32 v8, v240
	v_mov_b32_e32 v9, v241
	v_pk_mul_f32 v[6:7], v[18:19], v[6:7]
	v_pk_mul_f32 v[8:9], v[20:21], v[8:9]
	v_cvt_pk_bf16_f32 v6, v6, v7
	v_cvt_pk_bf16_f32 v7, v8, v9
	global_store_dwordx2 v[32:33], v[6:7], off offset:160
	v_pk_mul_f32 v[18:19], v[30:31], v[70:71] op_sel_hi:[1,0]
	v_pk_mul_f32 v[20:21], v[26:27], v[70:71] op_sel_hi:[1,0]
	v_mov_b32_e32 v6, v242
	v_mov_b32_e32 v7, v243
	v_mov_b32_e32 v8, v244
	v_mov_b32_e32 v9, v245
	v_pk_mul_f32 v[6:7], v[18:19], v[6:7]
	v_pk_mul_f32 v[8:9], v[20:21], v[8:9]
	v_cvt_pk_bf16_f32 v6, v6, v7
	v_cvt_pk_bf16_f32 v7, v8, v9
	global_store_dwordx2 v[32:33], v[6:7], off offset:176
	v_mov_b32_e32 v6, v246
	v_mov_b32_e32 v7, v247
	v_mov_b32_e32 v8, v248
	v_mov_b32_e32 v9, v249
	v_pk_mul_f32 v[2:3], v[2:3], v[6:7]
	v_pk_mul_f32 v[4:5], v[4:5], v[8:9]
	v_cvt_pk_bf16_f32 v2, v2, v3
	v_cvt_pk_bf16_f32 v3, v4, v5
	global_store_dwordx2 v[32:33], v[2:3], off offset:192
	global_load_dwordx4 v[226:229], v[144:145], off offset:416
	global_load_dwordx4 v[230:233], v[144:145], off offset:448
	global_load_dwordx4 v[234:237], v[144:145], off offset:480
	v_pk_mul_f32 v[6:7], v[84:85], v[70:71] op_sel_hi:[1,0]
	v_pk_mul_f32 v[8:9], v[86:87], v[70:71] op_sel_hi:[1,0]
	s_waitcnt vmcnt(0)
	v_mov_b32_e32 v2, v226
	v_mov_b32_e32 v3, v227
	v_mov_b32_e32 v4, v228
	v_mov_b32_e32 v5, v229
	v_pk_mul_f32 v[2:3], v[6:7], v[2:3]
	v_pk_mul_f32 v[4:5], v[8:9], v[4:5]
	v_cvt_pk_bf16_f32 v2, v2, v3
	v_cvt_pk_bf16_f32 v3, v4, v5
	global_store_dwordx2 v[32:33], v[2:3], off offset:208
	v_pk_mul_f32 v[6:7], v[10:11], v[70:71] op_sel_hi:[1,0]
	v_pk_mul_f32 v[8:9], v[12:13], v[70:71] op_sel_hi:[1,0]
	v_mov_b32_e32 v2, v230
	v_mov_b32_e32 v3, v231
	v_mov_b32_e32 v4, v232
	v_mov_b32_e32 v5, v233
	v_pk_mul_f32 v[2:3], v[6:7], v[2:3]
	v_pk_mul_f32 v[4:5], v[8:9], v[4:5]
	v_cvt_pk_bf16_f32 v2, v2, v3
	v_cvt_pk_bf16_f32 v3, v4, v5
	global_store_dwordx2 v[32:33], v[2:3], off offset:224
	v_pk_mul_f32 v[6:7], v[14:15], v[70:71] op_sel_hi:[1,0]
	v_pk_mul_f32 v[8:9], v[16:17], v[70:71] op_sel_hi:[1,0]
	v_mov_b32_e32 v2, v234
	v_mov_b32_e32 v3, v235
	v_mov_b32_e32 v4, v236
	v_mov_b32_e32 v5, v237
	v_pk_mul_f32 v[2:3], v[6:7], v[2:3]
	v_pk_mul_f32 v[4:5], v[8:9], v[4:5]
	v_cvt_pk_bf16_f32 v2, v2, v3
	v_cvt_pk_bf16_f32 v3, v4, v5
	global_store_dwordx2 v[32:33], v[2:3], off offset:240
	s_branch .LBB0_485

; DI bf16_t f2bf(float x) { return (bf16_t)(pack2(x, 0.f) & 0xffffu); }
; DI int crow(int i, int hh) { return (i & 3) + 8 * (i >> 2) + 4 * hh; }
;   DI void operator()(f32x16 (&acc)[2][4], int grow0, int gcol0, int lane, int w, char* lds) {
;     ...
;     const int part = gcol0 >> 10, cin = gcol0 & 1023;
;     if (part < 2) {
;       bf16_t* dst = part == 0 ? Q : K;
; #pragma unroll
;       for (int mt = 0; mt < 2; ++mt)
; #pragma unroll
;         for (int pr = 0; pr < 2; ++pr)
; #pragma unroll
;           for (int i = 0; i < 16; ++i) {
;             int row = grow0 + mt * 32 + crow(i, hh);
;             float c = cs[row * 32 + l31], s = sn[row * 32 + l31];
;             float x1 = acc[mt][2 * pr][i], x2 = acc[mt][2 * pr + 1][i];
;             int col = cin + pr * 64 + l31;
;             dst[(size_t)row * D_ + col] = f2bf(x1 * c - x2 * s);
;             dst[(size_t)row * D_ + col + 32] = f2bf(x2 * c + x1 * s);
;           }
.LBB0_524:
	s_andn2_saveexec_b64 s[44:45], s[6:7]
	s_cbranch_execz .LBB0_515
	s_movk_i32 s2, 0x400
	v_cmp_gt_u32_e32 vcc, s2, v132
	v_mov_b32_e32 v132, s81
	v_mov_b32_e32 v133, s79
	v_cndmask_b32_e32 v135, v132, v133, vcc
	v_mov_b32_e32 v132, s80
	v_mov_b32_e32 v133, s78
	v_cndmask_b32_e32 v134, v132, v133, vcc
	v_lshl_or_b32 v132, v130, 2, v0
	v_lshl_or_b32 v130, v132, 5, v138
	v_or_b32_e32 v0, v131, v138
	v_ashrrev_i32_e32 v131, 31, v130
	v_lshlrev_b64 v[136:137], 2, v[130:131]
	v_lshlrev_b32_e32 v0, 1, v0
	v_lshl_add_u64 v[130:131], v[134:135], 0, v[0:1]
	v_lshl_add_u64 v[134:135], s[18:19], 0, v[136:137]
	v_lshl_add_u64 v[140:141], s[16:17], 0, v[136:137]
	s_mov_b32 s100, 0x1000
	s_mov_b32 s101, 0
	global_load_dword v174, v[134:135], off
	global_load_dword v175, v[134:135], off offset:128
	global_load_dword v176, v[134:135], off offset:256
	global_load_dword v177, v[134:135], off offset:384
	global_load_dword v178, v[134:135], off offset:1024
	global_load_dword v179, v[134:135], off offset:1152
	global_load_dword v180, v[134:135], off offset:1280
	global_load_dword v181, v[134:135], off offset:1408
	global_load_dword v182, v[134:135], off offset:2048
	global_load_dword v183, v[134:135], off offset:2176
	global_load_dword v184, v[134:135], off offset:2304
	global_load_dword v185, v[134:135], off offset:2432
	global_load_dword v186, v[134:135], off offset:3072
	global_load_dword v187, v[134:135], off offset:3200
	global_load_dword v188, v[134:135], off offset:3328
	global_load_dword v189, v[134:135], off offset:3456
	v_lshl_add_u64 v[250:251], v[134:135], 0, s[100:101]
	global_load_dword v190, v[250:251], off
	global_load_dword v191, v[250:251], off offset:128
	global_load_dword v192, v[250:251], off offset:256
	global_load_dword v193, v[250:251], off offset:384
	global_load_dword v194, v[250:251], off offset:1024
	global_load_dword v195, v[250:251], off offset:1152
	global_load_dword v196, v[250:251], off offset:1280
	global_load_dword v197, v[250:251], off offset:1408
	global_load_dword v198, v[250:251], off offset:2048
	global_load_dword v199, v[250:251], off offset:2176
	global_load_dword v200, v[250:251], off offset:2304
	global_load_dword v201, v[250:251], off offset:2432
	global_load_dword v202, v[250:251], off offset:3072
	global_load_dword v203, v[250:251], off offset:3200
	global_load_dword v204, v[250:251], off offset:3328
	global_load_dword v205, v[250:251], off offset:3456
	global_load_dword v206, v[140:141], off
	global_load_dword v207, v[140:141], off offset:128
	global_load_dword v208, v[140:141], off offset:256
	global_load_dword v209, v[140:141], off offset:384
	global_load_dword v210, v[140:141], off offset:1024
	global_load_dword v211, v[140:141], off offset:1152
	global_load_dword v212, v[140:141], off offset:1280
	global_load_dword v213, v[140:141], off offset:1408
	global_load_dword v226, v[140:141], off offset:2048
	global_load_dword v227, v[140:141], off offset:2176
	global_load_dword v228, v[140:141], off offset:2304
	global_load_dword v229, v[140:141], off offset:2432
	global_load_dword v230, v[140:141], off offset:3072
	global_load_dword v231, v[140:141], off offset:3200
	global_load_dword v232, v[140:141], off offset:3328
	global_load_dword v233, v[140:141], off offset:3456
	v_lshl_add_u64 v[250:251], v[140:141], 0, s[100:101]
	global_load_dword v234, v[250:251], off
	global_load_dword v235, v[250:251], off offset:128
	global_load_dword v236, v[250:251], off offset:256
	global_load_dword v237, v[250:251], off offset:384
	global_load_dword v238, v[250:251], off offset:1024
	global_load_dword v239, v[250:251], off offset:1152
	global_load_dword v240, v[250:251], off offset:1280
	global_load_dword v241, v[250:251], off offset:1408
	global_load_dword v242, v[250:251], off offset:2048
	global_load_dword v243, v[250:251], off offset:2176
	global_load_dword v244, v[250:251], off offset:2304
	global_load_dword v245, v[250:251], off offset:2432
	global_load_dword v246, v[250:251], off offset:3072
	global_load_dword v247, v[250:251], off offset:3200
	global_load_dword v248, v[250:251], off offset:3328
	global_load_dword v249, v[250:251], off offset:3456
	s_waitcnt vmcnt(0)
	v_mov_b32_e32 v139, v174
	v_mov_b32_e32 v0, v206
	v_mul_f32_e32 v133, v98, v139
	v_fma_f32 v133, v114, v0, -v133
	v_cvt_pk_bf16_f32 v136, v133, s0
	v_ashrrev_i32_e32 v133, 31, v132
	v_lshlrev_b64 v[134:135], 11, v[132:133]
	v_lshl_add_u64 v[134:135], v[130:131], 0, v[134:135]
	global_store_short v[134:135], v136, off
	v_or_b32_e32 v136, 1, v132
	v_lshl_or_b32 v140, v136, 5, v138
	v_ashrrev_i32_e32 v141, 31, v140
	v_lshlrev_b64 v[140:141], 2, v[140:141]
	v_lshl_add_u64 v[142:143], s[16:17], 0, v[140:141]
	v_lshl_add_u64 v[140:141], s[18:19], 0, v[140:141]
	v_mov_b32_e32 v140, v175
	v_mul_f32_e32 v114, v114, v139
	v_mov_b32_e32 v133, v207
	v_fmac_f32_e32 v114, v98, v0
	v_cvt_pk_bf16_f32 v98, v114, s0
	global_store_short v[134:135], v98, off offset:64
	v_ashrrev_i32_e32 v137, 31, v136
	v_lshlrev_b64 v[136:137], 11, v[136:137]
	v_lshl_add_u64 v[136:137], v[130:131], 0, v[136:137]
	v_mul_f32_e32 v98, v99, v140
	v_fma_f32 v98, v115, v133, -v98
	v_cvt_pk_bf16_f32 v98, v98, s0
	global_store_short v[136:137], v98, off
	v_mul_f32_e32 v98, v115, v140
	v_fmac_f32_e32 v98, v99, v133
	v_cvt_pk_bf16_f32 v98, v98, s0
	global_store_short v[136:137], v98, off offset:64
	v_or_b32_e32 v98, 2, v132
	v_lshl_or_b32 v114, v98, 5, v138
	v_ashrrev_i32_e32 v115, 31, v114
	v_lshlrev_b64 v[114:115], 2, v[114:115]
	v_lshl_add_u64 v[142:143], s[16:17], 0, v[114:115]
	v_lshl_add_u64 v[114:115], s[18:19], 0, v[114:115]
	v_mov_b32_e32 v141, v208
	s_nop 0
	v_mov_b32_e32 v142, v176
; DI bf16_t f2bf(float x) { return (bf16_t)(pack2(x, 0.f) & 0xffffu); }
; DI int crow(int i, int hh) { return (i & 3) + 8 * (i >> 2) + 4 * hh; }
;   DI void operator()(f32x16 (&acc)[2][4], int grow0, int gcol0, int lane, int w, char* lds) {
;     ...
;     const int part = gcol0 >> 10, cin = gcol0 & 1023;
;     if (part < 2) {
;       bf16_t* dst = part == 0 ? Q : K;
; #pragma unroll
;       for (int mt = 0; mt < 2; ++mt)
; #pragma unroll
;         for (int pr = 0; pr < 2; ++pr)
; #pragma unroll
;           for (int i = 0; i < 16; ++i) {
;             int row = grow0 + mt * 32 + crow(i, hh);
;             float c = cs[row * 32 + l31], s = sn[row * 32 + l31];
;             float x1 = acc[mt][2 * pr][i], x2 = acc[mt][2 * pr + 1][i];
;             int col = cin + pr * 64 + l31;
;             dst[(size_t)row * D_ + col] = f2bf(x1 * c - x2 * s);
;             dst[(size_t)row * D_ + col + 32] = f2bf(x2 * c + x1 * s);
;           }
	v_mul_f32_e32 v99, v100, v142
	v_fma_f32 v99, v116, v141, -v99
	v_cvt_pk_bf16_f32 v114, v99, s0
	v_ashrrev_i32_e32 v99, 31, v98
	v_lshlrev_b64 v[98:99], 11, v[98:99]
	v_lshl_add_u64 v[98:99], v[130:131], 0, v[98:99]
	global_store_short v[98:99], v114, off
	v_mul_f32_e32 v114, v116, v142
	v_fmac_f32_e32 v114, v100, v141
	v_cvt_pk_bf16_f32 v100, v114, s0
	v_or_b32_e32 v114, 3, v132
	v_lshl_or_b32 v144, v114, 5, v138
	v_ashrrev_i32_e32 v145, 31, v144
	v_lshlrev_b64 v[144:145], 2, v[144:145]
	v_lshl_add_u64 v[146:147], s[16:17], 0, v[144:145]
	v_lshl_add_u64 v[144:145], s[18:19], 0, v[144:145]
	v_mov_b32_e32 v144, v177
	v_ashrrev_i32_e32 v115, 31, v114
	v_mov_b32_e32 v143, v209
	v_lshlrev_b64 v[114:115], 11, v[114:115]
	global_store_short v[98:99], v100, off offset:64
	v_lshl_add_u64 v[114:115], v[130:131], 0, v[114:115]
	v_mul_f32_e32 v100, v101, v144
	v_fma_f32 v100, v117, v143, -v100
	v_cvt_pk_bf16_f32 v100, v100, s0
	global_store_short v[114:115], v100, off
	v_mul_f32_e32 v100, v117, v144
	v_fmac_f32_e32 v100, v101, v143
	v_cvt_pk_bf16_f32 v100, v100, s0
	global_store_short v[114:115], v100, off offset:64
	v_or_b32_e32 v100, 8, v132
	v_lshl_or_b32 v116, v100, 5, v138
	v_ashrrev_i32_e32 v117, 31, v116
	v_lshlrev_b64 v[116:117], 2, v[116:117]
	v_lshl_add_u64 v[146:147], s[16:17], 0, v[116:117]
	v_lshl_add_u64 v[116:117], s[18:19], 0, v[116:117]
	v_mov_b32_e32 v145, v210
	s_nop 0
	v_mov_b32_e32 v146, v178
	v_mul_f32_e32 v101, v102, v146
	v_fma_f32 v101, v118, v145, -v101
	v_cvt_pk_bf16_f32 v116, v101, s0
	v_ashrrev_i32_e32 v101, 31, v100
	v_lshlrev_b64 v[100:101], 11, v[100:101]
	v_lshl_add_u64 v[100:101], v[130:131], 0, v[100:101]
	global_store_short v[100:101], v116, off
	v_mul_f32_e32 v116, v118, v146
	v_fmac_f32_e32 v116, v102, v145
	v_cvt_pk_bf16_f32 v102, v116, s0
	v_or_b32_e32 v116, 9, v132
	v_lshl_or_b32 v148, v116, 5, v138
	v_ashrrev_i32_e32 v149, 31, v148
	v_lshlrev_b64 v[148:149], 2, v[148:149]
	v_lshl_add_u64 v[150:151], s[16:17], 0, v[148:149]
	v_lshl_add_u64 v[148:149], s[18:19], 0, v[148:149]
	v_mov_b32_e32 v148, v179
	v_ashrrev_i32_e32 v117, 31, v116
	v_mov_b32_e32 v147, v211
	v_lshlrev_b64 v[116:117], 11, v[116:117]
	global_store_short v[100:101], v102, off offset:64
	v_lshl_add_u64 v[116:117], v[130:131], 0, v[116:117]
	v_mul_f32_e32 v102, v103, v148
	v_fma_f32 v102, v119, v147, -v102
	v_cvt_pk_bf16_f32 v102, v102, s0
	global_store_short v[116:117], v102, off
	v_mul_f32_e32 v102, v119, v148
	v_fmac_f32_e32 v102, v103, v147
	v_cvt_pk_bf16_f32 v102, v102, s0
	global_store_short v[116:117], v102, off offset:64
	v_or_b32_e32 v102, 10, v132
	v_lshl_or_b32 v118, v102, 5, v138
	v_ashrrev_i32_e32 v119, 31, v118
	v_lshlrev_b64 v[118:119], 2, v[118:119]
	v_lshl_add_u64 v[150:151], s[16:17], 0, v[118:119]
	v_lshl_add_u64 v[118:119], s[18:19], 0, v[118:119]
	v_mov_b32_e32 v149, v212
	s_nop 0
	v_mov_b32_e32 v150, v180
	v_mul_f32_e32 v103, v104, v150
	v_fma_f32 v103, v120, v149, -v103
	v_cvt_pk_bf16_f32 v118, v103, s0
	v_ashrrev_i32_e32 v103, 31, v102
	v_lshlrev_b64 v[102:103], 11, v[102:103]
	v_lshl_add_u64 v[102:103], v[130:131], 0, v[102:103]
	global_store_short v[102:103], v118, off
	v_mul_f32_e32 v118, v120, v150
	v_fmac_f32_e32 v118, v104, v149
	v_cvt_pk_bf16_f32 v104, v118, s0
	v_or_b32_e32 v118, 11, v132
	v_lshl_or_b32 v152, v118, 5, v138
	v_ashrrev_i32_e32 v153, 31, v152
	v_lshlrev_b64 v[152:153], 2, v[152:153]
	v_lshl_add_u64 v[154:155], s[16:17], 0, v[152:153]
	v_lshl_add_u64 v[152:153], s[18:19], 0, v[152:153]
	v_mov_b32_e32 v152, v181
	v_ashrrev_i32_e32 v119, 31, v118
	v_mov_b32_e32 v151, v213
	v_lshlrev_b64 v[118:119], 11, v[118:119]
	global_store_short v[102:103], v104, off offset:64
	v_lshl_add_u64 v[118:119], v[130:131], 0, v[118:119]
	v_mul_f32_e32 v104, v105, v152
	v_fma_f32 v104, v121, v151, -v104
	v_cvt_pk_bf16_f32 v104, v104, s0
	global_store_short v[118:119], v104, off
	v_mul_f32_e32 v104, v121, v152
	v_fmac_f32_e32 v104, v105, v151
	v_cvt_pk_bf16_f32 v104, v104, s0
	global_store_short v[118:119], v104, off offset:64
	v_or_b32_e32 v104, 16, v132
	v_lshl_or_b32 v120, v104, 5, v138
	v_ashrrev_i32_e32 v121, 31, v120
	v_lshlrev_b64 v[120:121], 2, v[120:121]
	v_lshl_add_u64 v[154:155], s[16:17], 0, v[120:121]
	v_lshl_add_u64 v[120:121], s[18:19], 0, v[120:121]
	v_mov_b32_e32 v153, v226
	s_nop 0
	v_mov_b32_e32 v154, v182
	v_mul_f32_e32 v105, v106, v154
	v_fma_f32 v105, v122, v153, -v105
	v_cvt_pk_bf16_f32 v120, v105, s0
	v_ashrrev_i32_e32 v105, 31, v104
	v_lshlrev_b64 v[104:105], 11, v[104:105]
	v_lshl_add_u64 v[104:105], v[130:131], 0, v[104:105]
	global_store_short v[104:105], v120, off
	v_mul_f32_e32 v120, v122, v154
	v_fmac_f32_e32 v120, v106, v153
	v_cvt_pk_bf16_f32 v106, v120, s0
	v_or_b32_e32 v120, 17, v132
	v_lshl_or_b32 v156, v120, 5, v138
	v_ashrrev_i32_e32 v157, 31, v156
	v_lshlrev_b64 v[156:157], 2, v[156:157]
	v_lshl_add_u64 v[158:159], s[16:17], 0, v[156:157]
	v_lshl_add_u64 v[156:157], s[18:19], 0, v[156:157]
	v_mov_b32_e32 v156, v183
	v_ashrrev_i32_e32 v121, 31, v120
	v_mov_b32_e32 v155, v227
	v_lshlrev_b64 v[120:121], 11, v[120:121]
	global_store_short v[104:105], v106, off offset:64
	v_lshl_add_u64 v[120:121], v[130:131], 0, v[120:121]
	v_mul_f32_e32 v106, v107, v156
	v_fma_f32 v106, v123, v155, -v106
	v_cvt_pk_bf16_f32 v106, v106, s0
	global_store_short v[120:121], v106, off
	v_mul_f32_e32 v106, v123, v156
	v_fmac_f32_e32 v106, v107, v155
	v_cvt_pk_bf16_f32 v106, v106, s0
	global_store_short v[120:121], v106, off offset:64
	v_or_b32_e32 v106, 18, v132
	v_lshl_or_b32 v122, v106, 5, v138
	v_ashrrev_i32_e32 v123, 31, v122
	v_lshlrev_b64 v[122:123], 2, v[122:123]
	v_lshl_add_u64 v[158:159], s[16:17], 0, v[122:123]
; DI bf16_t f2bf(float x) { return (bf16_t)(pack2(x, 0.f) & 0xffffu); }
; DI int crow(int i, int hh) { return (i & 3) + 8 * (i >> 2) + 4 * hh; }
;   DI void operator()(f32x16 (&acc)[2][4], int grow0, int gcol0, int lane, int w, char* lds) {
;     ...
;     const int part = gcol0 >> 10, cin = gcol0 & 1023;
;     if (part < 2) {
;       bf16_t* dst = part == 0 ? Q : K;
; #pragma unroll
;       for (int mt = 0; mt < 2; ++mt)
; #pragma unroll
;         for (int pr = 0; pr < 2; ++pr)
; #pragma unroll
;           for (int i = 0; i < 16; ++i) {
;             int row = grow0 + mt * 32 + crow(i, hh);
;             float c = cs[row * 32 + l31], s = sn[row * 32 + l31];
;             float x1 = acc[mt][2 * pr][i], x2 = acc[mt][2 * pr + 1][i];
;             int col = cin + pr * 64 + l31;
;             dst[(size_t)row * D_ + col] = f2bf(x1 * c - x2 * s);
;             dst[(size_t)row * D_ + col + 32] = f2bf(x2 * c + x1 * s);
;           }
	v_lshl_add_u64 v[122:123], s[18:19], 0, v[122:123]
	v_mov_b32_e32 v157, v228
	s_nop 0
	v_mov_b32_e32 v158, v184
	v_mul_f32_e32 v107, v108, v158
	v_fma_f32 v107, v124, v157, -v107
	v_cvt_pk_bf16_f32 v122, v107, s0
	v_ashrrev_i32_e32 v107, 31, v106
	v_lshlrev_b64 v[106:107], 11, v[106:107]
	v_lshl_add_u64 v[106:107], v[130:131], 0, v[106:107]
	global_store_short v[106:107], v122, off
	v_mul_f32_e32 v122, v124, v158
	v_fmac_f32_e32 v122, v108, v157
	v_cvt_pk_bf16_f32 v108, v122, s0
	v_or_b32_e32 v122, 19, v132
	v_lshl_or_b32 v160, v122, 5, v138
	v_ashrrev_i32_e32 v161, 31, v160
	v_lshlrev_b64 v[160:161], 2, v[160:161]
	v_lshl_add_u64 v[166:167], s[16:17], 0, v[160:161]
	v_lshl_add_u64 v[160:161], s[18:19], 0, v[160:161]
	v_mov_b32_e32 v160, v185
	v_ashrrev_i32_e32 v123, 31, v122
	v_mov_b32_e32 v159, v229
	v_lshlrev_b64 v[122:123], 11, v[122:123]
	global_store_short v[106:107], v108, off offset:64
	v_lshl_add_u64 v[122:123], v[130:131], 0, v[122:123]
	v_mul_f32_e32 v108, v109, v160
	v_fma_f32 v108, v125, v159, -v108
	v_cvt_pk_bf16_f32 v108, v108, s0
	global_store_short v[122:123], v108, off
	v_mul_f32_e32 v108, v125, v160
	v_fmac_f32_e32 v108, v109, v159
	v_cvt_pk_bf16_f32 v108, v108, s0
	global_store_short v[122:123], v108, off offset:64
	v_or_b32_e32 v108, 24, v132
	v_lshl_or_b32 v124, v108, 5, v138
	v_ashrrev_i32_e32 v125, 31, v124
	v_lshlrev_b64 v[124:125], 2, v[124:125]
	v_lshl_add_u64 v[166:167], s[16:17], 0, v[124:125]
	v_lshl_add_u64 v[124:125], s[18:19], 0, v[124:125]
	v_mov_b32_e32 v163, v186
	v_mov_b32_e32 v161, v230
	v_mul_f32_e32 v109, v110, v163
	v_fma_f32 v109, v126, v161, -v109
	v_cvt_pk_bf16_f32 v124, v109, s0
	v_ashrrev_i32_e32 v109, 31, v108
	v_lshlrev_b64 v[108:109], 11, v[108:109]
	v_lshl_add_u64 v[108:109], v[130:131], 0, v[108:109]
	global_store_short v[108:109], v124, off
	v_mul_f32_e32 v124, v126, v163
	v_fmac_f32_e32 v124, v110, v161
	v_cvt_pk_bf16_f32 v110, v124, s0
	v_or_b32_e32 v124, 25, v132
	v_lshl_or_b32 v166, v124, 5, v138
	v_ashrrev_i32_e32 v167, 31, v166
	v_lshlrev_b64 v[166:167], 2, v[166:167]
	v_lshl_add_u64 v[168:169], s[16:17], 0, v[166:167]
	v_lshl_add_u64 v[166:167], s[18:19], 0, v[166:167]
	v_mov_b32_e32 v166, v187
	v_ashrrev_i32_e32 v125, 31, v124
	v_mov_b32_e32 v164, v231
	v_lshlrev_b64 v[124:125], 11, v[124:125]
	global_store_short v[108:109], v110, off offset:64
	v_lshl_add_u64 v[124:125], v[130:131], 0, v[124:125]
	v_mul_f32_e32 v110, v111, v166
	v_fma_f32 v110, v127, v164, -v110
	v_cvt_pk_bf16_f32 v110, v110, s0
	global_store_short v[124:125], v110, off
	v_mul_f32_e32 v110, v127, v166
	v_fmac_f32_e32 v110, v111, v164
	v_cvt_pk_bf16_f32 v110, v110, s0
	global_store_short v[124:125], v110, off offset:64
	v_or_b32_e32 v110, 26, v132
	v_lshl_or_b32 v126, v110, 5, v138
	v_ashrrev_i32_e32 v127, 31, v126
	v_lshlrev_b64 v[126:127], 2, v[126:127]
	v_lshl_add_u64 v[168:169], s[16:17], 0, v[126:127]
	v_lshl_add_u64 v[126:127], s[18:19], 0, v[126:127]
	v_mov_b32_e32 v167, v232
	s_nop 0
	v_mov_b32_e32 v168, v188
	v_mul_f32_e32 v111, v112, v168
	v_fma_f32 v111, v128, v167, -v111
	v_cvt_pk_bf16_f32 v126, v111, s0
	v_ashrrev_i32_e32 v111, 31, v110
	v_lshlrev_b64 v[110:111], 11, v[110:111]
	v_lshl_add_u64 v[110:111], v[130:131], 0, v[110:111]
	global_store_short v[110:111], v126, off
	v_mul_f32_e32 v126, v128, v168
	v_fmac_f32_e32 v126, v112, v167
	v_cvt_pk_bf16_f32 v112, v126, s0
	v_or_b32_e32 v126, 27, v132
	v_lshl_or_b32 v170, v126, 5, v138
	v_ashrrev_i32_e32 v171, 31, v170
	v_lshlrev_b64 v[170:171], 2, v[170:171]
	v_lshl_add_u64 v[172:173], s[16:17], 0, v[170:171]
	v_lshl_add_u64 v[170:171], s[18:19], 0, v[170:171]
	v_mov_b32_e32 v128, v189
	v_mul_f32_e32 v127, v113, v128
	global_store_short v[110:111], v112, off offset:64
	v_mov_b32_e32 v112, v233
	v_fma_f32 v127, v129, v112, -v127
	v_cvt_pk_bf16_f32 v169, v127, s0
	v_ashrrev_i32_e32 v127, 31, v126
	v_mul_f32_e32 v129, v129, v128
	v_lshlrev_b64 v[126:127], 11, v[126:127]
	v_fmac_f32_e32 v129, v113, v112
	v_lshl_add_u64 v[126:127], v[130:131], 0, v[126:127]
	v_cvt_pk_bf16_f32 v113, v129, s0
	global_store_short v[126:127], v113, off offset:64
	v_mul_f32_e32 v113, v66, v139
	v_fma_f32 v113, v82, v0, -v113
	v_mul_f32_e32 v82, v82, v139
	v_fmac_f32_e32 v82, v66, v0
	v_cvt_pk_bf16_f32 v0, v82, s0
	global_store_short v[134:135], v0, off offset:192
	v_mul_f32_e32 v0, v67, v140
	v_fma_f32 v0, v83, v133, -v0
	v_cvt_pk_bf16_f32 v0, v0, s0
	global_store_short v[136:137], v0, off offset:128
	v_mul_f32_e32 v0, v83, v140
	v_fmac_f32_e32 v0, v67, v133
	v_cvt_pk_bf16_f32 v0, v0, s0
	global_store_short v[136:137], v0, off offset:192
	v_mul_f32_e32 v0, v68, v142
	v_fma_f32 v0, v84, v141, -v0
	v_cvt_pk_bf16_f32 v0, v0, s0
	global_store_short v[98:99], v0, off offset:128
	v_mul_f32_e32 v0, v84, v142
	v_fmac_f32_e32 v0, v68, v141
	v_cvt_pk_bf16_f32 v0, v0, s0
	global_store_short v[98:99], v0, off offset:192
	v_mul_f32_e32 v0, v69, v144
	v_fma_f32 v0, v85, v143, -v0
	v_cvt_pk_bf16_f32 v0, v0, s0
	global_store_short v[114:115], v0, off offset:128
	v_mul_f32_e32 v0, v85, v144
	v_fmac_f32_e32 v0, v69, v143
	v_cvt_pk_bf16_f32 v0, v0, s0
	global_store_short v[114:115], v0, off offset:192
	v_mul_f32_e32 v0, v70, v146
	v_fma_f32 v0, v86, v145, -v0
	v_cvt_pk_bf16_f32 v0, v0, s0
	global_store_short v[100:101], v0, off offset:128
	v_mul_f32_e32 v0, v86, v146
	v_fmac_f32_e32 v0, v70, v145
	v_cvt_pk_bf16_f32 v0, v0, s0
	global_store_short v[100:101], v0, off offset:192
	v_mul_f32_e32 v0, v71, v148
	v_fma_f32 v0, v87, v147, -v0
	v_cvt_pk_bf16_f32 v0, v0, s0
	global_store_short v[116:117], v0, off offset:128
	v_mul_f32_e32 v0, v87, v148
	v_fmac_f32_e32 v0, v71, v147
	v_cvt_pk_bf16_f32 v0, v0, s0
; DI bf16_t f2bf(float x) { return (bf16_t)(pack2(x, 0.f) & 0xffffu); }
; DI int crow(int i, int hh) { return (i & 3) + 8 * (i >> 2) + 4 * hh; }
;   DI void operator()(f32x16 (&acc)[2][4], int grow0, int gcol0, int lane, int w, char* lds) {
;     ...
;     const int part = gcol0 >> 10, cin = gcol0 & 1023;
;     if (part < 2) {
;       bf16_t* dst = part == 0 ? Q : K;
; #pragma unroll
;       for (int mt = 0; mt < 2; ++mt)
; #pragma unroll
;         for (int pr = 0; pr < 2; ++pr)
; #pragma unroll
;           for (int i = 0; i < 16; ++i) {
;             int row = grow0 + mt * 32 + crow(i, hh);
;             float c = cs[row * 32 + l31], s = sn[row * 32 + l31];
;             float x1 = acc[mt][2 * pr][i], x2 = acc[mt][2 * pr + 1][i];
;             int col = cin + pr * 64 + l31;
;             dst[(size_t)row * D_ + col] = f2bf(x1 * c - x2 * s);
;             dst[(size_t)row * D_ + col + 32] = f2bf(x2 * c + x1 * s);
;           }
	global_store_short v[116:117], v0, off offset:192
	v_mul_f32_e32 v0, v72, v150
	v_fma_f32 v0, v88, v149, -v0
	v_cvt_pk_bf16_f32 v0, v0, s0
	global_store_short v[102:103], v0, off offset:128
	v_mul_f32_e32 v0, v88, v150
	v_fmac_f32_e32 v0, v72, v149
	v_cvt_pk_bf16_f32 v0, v0, s0
	global_store_short v[102:103], v0, off offset:192
	v_mul_f32_e32 v0, v73, v152
	v_fma_f32 v0, v89, v151, -v0
	v_cvt_pk_bf16_f32 v0, v0, s0
	global_store_short v[118:119], v0, off offset:128
	v_mul_f32_e32 v0, v89, v152
	v_fmac_f32_e32 v0, v73, v151
	v_cvt_pk_bf16_f32 v0, v0, s0
	global_store_short v[118:119], v0, off offset:192
	v_mul_f32_e32 v0, v74, v154
	v_fma_f32 v0, v90, v153, -v0
	v_cvt_pk_bf16_f32 v0, v0, s0
	global_store_short v[104:105], v0, off offset:128
	v_mul_f32_e32 v0, v90, v154
	v_fmac_f32_e32 v0, v74, v153
	v_cvt_pk_bf16_f32 v0, v0, s0
	global_store_short v[104:105], v0, off offset:192
	v_mul_f32_e32 v0, v75, v156
	v_fma_f32 v0, v91, v155, -v0
	v_cvt_pk_bf16_f32 v0, v0, s0
	global_store_short v[120:121], v0, off offset:128
	v_mul_f32_e32 v0, v91, v156
	v_fmac_f32_e32 v0, v75, v155
	v_cvt_pk_bf16_f32 v0, v0, s0
	global_store_short v[120:121], v0, off offset:192
	v_mul_f32_e32 v0, v76, v158
	v_fma_f32 v0, v92, v157, -v0
	v_cvt_pk_bf16_f32 v0, v0, s0
	global_store_short v[106:107], v0, off offset:128
	v_mul_f32_e32 v0, v92, v158
	v_fmac_f32_e32 v0, v76, v157
	v_cvt_pk_bf16_f32 v0, v0, s0
	global_store_short v[106:107], v0, off offset:192
	v_mul_f32_e32 v0, v77, v160
	v_fma_f32 v0, v93, v159, -v0
	v_cvt_pk_bf16_f32 v0, v0, s0
	global_store_short v[122:123], v0, off offset:128
	v_mul_f32_e32 v0, v93, v160
	v_fmac_f32_e32 v0, v77, v159
	v_cvt_pk_bf16_f32 v0, v0, s0
	global_store_short v[122:123], v0, off offset:192
	v_mul_f32_e32 v0, v78, v163
	v_fma_f32 v0, v94, v161, -v0
	v_cvt_pk_bf16_f32 v0, v0, s0
	global_store_short v[108:109], v0, off offset:128
	v_mul_f32_e32 v0, v94, v163
	v_fmac_f32_e32 v0, v78, v161
	v_cvt_pk_bf16_f32 v0, v0, s0
	global_store_short v[108:109], v0, off offset:192
	v_mul_f32_e32 v0, v79, v166
	v_fma_f32 v0, v95, v164, -v0
	v_cvt_pk_bf16_f32 v0, v0, s0
	global_store_short v[124:125], v0, off offset:128
	v_mul_f32_e32 v0, v95, v166
	v_fmac_f32_e32 v0, v79, v164
	v_cvt_pk_bf16_f32 v0, v0, s0
	global_store_short v[124:125], v0, off offset:192
	v_mul_f32_e32 v0, v80, v168
	v_fma_f32 v0, v96, v167, -v0
	v_cvt_pk_bf16_f32 v0, v0, s0
	global_store_short v[110:111], v0, off offset:128
	v_mul_f32_e32 v0, v96, v168
	v_fmac_f32_e32 v0, v80, v167
	v_cvt_pk_bf16_f32 v0, v0, s0
	global_store_short v[110:111], v0, off offset:192
	v_mul_f32_e32 v0, v81, v128
	v_fma_f32 v0, v97, v112, -v0
	v_or_b32_e32 v66, 32, v132
	v_cvt_pk_bf16_f32 v0, v0, s0
	v_lshl_or_b32 v68, v66, 5, v138
	global_store_short v[126:127], v0, off offset:128
	v_mul_f32_e32 v0, v97, v128
	v_ashrrev_i32_e32 v69, 31, v68
	v_fmac_f32_e32 v0, v81, v112
	v_lshlrev_b64 v[68:69], 2, v[68:69]
	v_cvt_pk_bf16_f32 v0, v0, s0
	v_lshl_add_u64 v[70:71], s[16:17], 0, v[68:69]
	v_lshl_add_u64 v[68:69], s[18:19], 0, v[68:69]
	global_store_short v[126:127], v0, off offset:192
	v_mov_b32_e32 v0, v234
	v_cvt_pk_bf16_f32 v113, v113, s0
	v_mov_b32_e32 v70, v190
	v_mul_f32_e32 v67, v34, v70
	v_fma_f32 v67, v50, v0, -v67
	v_cvt_pk_bf16_f32 v68, v67, s0
	v_ashrrev_i32_e32 v67, 31, v66
	v_lshlrev_b64 v[66:67], 11, v[66:67]
	v_lshl_add_u64 v[66:67], v[130:131], 0, v[66:67]
	global_store_short v[66:67], v68, off
	v_or_b32_e32 v68, 33, v132
	v_lshl_or_b32 v72, v68, 5, v138
	v_ashrrev_i32_e32 v73, 31, v72
	v_lshlrev_b64 v[72:73], 2, v[72:73]
	v_lshl_add_u64 v[74:75], s[16:17], 0, v[72:73]
	v_lshl_add_u64 v[72:73], s[18:19], 0, v[72:73]
	v_mov_b32_e32 v72, v191
	v_mul_f32_e32 v50, v50, v70
	v_mov_b32_e32 v71, v235
	v_fmac_f32_e32 v50, v34, v0
	v_cvt_pk_bf16_f32 v34, v50, s0
	global_store_short v[66:67], v34, off offset:64
	v_ashrrev_i32_e32 v69, 31, v68
	v_lshlrev_b64 v[68:69], 11, v[68:69]
	v_lshl_add_u64 v[68:69], v[130:131], 0, v[68:69]
	global_store_short v[126:127], v169, off
	global_store_short v[134:135], v113, off offset:128
	v_mul_f32_e32 v34, v35, v72
	v_fma_f32 v34, v51, v71, -v34
	v_cvt_pk_bf16_f32 v34, v34, s0
	global_store_short v[68:69], v34, off
	v_mul_f32_e32 v34, v51, v72
	v_fmac_f32_e32 v34, v35, v71
	v_cvt_pk_bf16_f32 v34, v34, s0
	global_store_short v[68:69], v34, off offset:64
	v_or_b32_e32 v34, 34, v132
	v_lshl_or_b32 v50, v34, 5, v138
	v_ashrrev_i32_e32 v51, 31, v50
	v_lshlrev_b64 v[50:51], 2, v[50:51]
	v_lshl_add_u64 v[74:75], s[16:17], 0, v[50:51]
	v_lshl_add_u64 v[50:51], s[18:19], 0, v[50:51]
	v_mov_b32_e32 v73, v236
	s_nop 0
	v_mov_b32_e32 v74, v192
	v_mul_f32_e32 v35, v36, v74
	v_fma_f32 v35, v52, v73, -v35
	v_cvt_pk_bf16_f32 v50, v35, s0
	v_ashrrev_i32_e32 v35, 31, v34
	v_lshlrev_b64 v[34:35], 11, v[34:35]
	v_lshl_add_u64 v[34:35], v[130:131], 0, v[34:35]
	global_store_short v[34:35], v50, off
	v_mul_f32_e32 v50, v52, v74
	v_fmac_f32_e32 v50, v36, v73
	v_cvt_pk_bf16_f32 v36, v50, s0
	v_or_b32_e32 v50, 35, v132
	v_lshl_or_b32 v76, v50, 5, v138
	v_ashrrev_i32_e32 v77, 31, v76
	v_lshlrev_b64 v[76:77], 2, v[76:77]
	v_lshl_add_u64 v[78:79], s[16:17], 0, v[76:77]
	v_lshl_add_u64 v[76:77], s[18:19], 0, v[76:77]
	v_mov_b32_e32 v76, v193
	v_ashrrev_i32_e32 v51, 31, v50
	v_mov_b32_e32 v75, v237
	v_lshlrev_b64 v[50:51], 11, v[50:51]
	global_store_short v[34:35], v36, off offset:64
	v_lshl_add_u64 v[50:51], v[130:131], 0, v[50:51]
	v_mul_f32_e32 v36, v37, v76
	v_fma_f32 v36, v53, v75, -v36
	v_cvt_pk_bf16_f32 v36, v36, s0
	global_store_short v[50:51], v36, off
	v_mul_f32_e32 v36, v53, v76
	v_fmac_f32_e32 v36, v37, v75
	v_cvt_pk_bf16_f32 v36, v36, s0
	global_store_short v[50:51], v36, off offset:64
; DI bf16_t f2bf(float x) { return (bf16_t)(pack2(x, 0.f) & 0xffffu); }
; DI int crow(int i, int hh) { return (i & 3) + 8 * (i >> 2) + 4 * hh; }
;   DI void operator()(f32x16 (&acc)[2][4], int grow0, int gcol0, int lane, int w, char* lds) {
;     ...
;     const int part = gcol0 >> 10, cin = gcol0 & 1023;
;     if (part < 2) {
;       bf16_t* dst = part == 0 ? Q : K;
; #pragma unroll
;       for (int mt = 0; mt < 2; ++mt)
; #pragma unroll
;         for (int pr = 0; pr < 2; ++pr)
; #pragma unroll
;           for (int i = 0; i < 16; ++i) {
;             int row = grow0 + mt * 32 + crow(i, hh);
;             float c = cs[row * 32 + l31], s = sn[row * 32 + l31];
;             float x1 = acc[mt][2 * pr][i], x2 = acc[mt][2 * pr + 1][i];
;             int col = cin + pr * 64 + l31;
;             dst[(size_t)row * D_ + col] = f2bf(x1 * c - x2 * s);
;             dst[(size_t)row * D_ + col + 32] = f2bf(x2 * c + x1 * s);
;           }
	v_or_b32_e32 v36, 40, v132
	v_lshl_or_b32 v52, v36, 5, v138
	v_ashrrev_i32_e32 v53, 31, v52
	v_lshlrev_b64 v[52:53], 2, v[52:53]
	v_lshl_add_u64 v[78:79], s[16:17], 0, v[52:53]
	v_lshl_add_u64 v[52:53], s[18:19], 0, v[52:53]
	v_mov_b32_e32 v77, v238
	s_nop 0
	v_mov_b32_e32 v78, v194
	v_mul_f32_e32 v37, v38, v78
	v_fma_f32 v37, v54, v77, -v37
	v_cvt_pk_bf16_f32 v52, v37, s0
	v_ashrrev_i32_e32 v37, 31, v36
	v_lshlrev_b64 v[36:37], 11, v[36:37]
	v_lshl_add_u64 v[36:37], v[130:131], 0, v[36:37]
	global_store_short v[36:37], v52, off
	v_mul_f32_e32 v52, v54, v78
	v_fmac_f32_e32 v52, v38, v77
	v_cvt_pk_bf16_f32 v38, v52, s0
	v_or_b32_e32 v52, 41, v132
	v_lshl_or_b32 v80, v52, 5, v138
	v_ashrrev_i32_e32 v81, 31, v80
	v_lshlrev_b64 v[80:81], 2, v[80:81]
	v_lshl_add_u64 v[82:83], s[16:17], 0, v[80:81]
	v_lshl_add_u64 v[80:81], s[18:19], 0, v[80:81]
	v_mov_b32_e32 v80, v195
	v_ashrrev_i32_e32 v53, 31, v52
	v_mov_b32_e32 v79, v239
	v_lshlrev_b64 v[52:53], 11, v[52:53]
	global_store_short v[36:37], v38, off offset:64
	v_lshl_add_u64 v[52:53], v[130:131], 0, v[52:53]
	v_mul_f32_e32 v38, v39, v80
	v_fma_f32 v38, v55, v79, -v38
	v_cvt_pk_bf16_f32 v38, v38, s0
	global_store_short v[52:53], v38, off
	v_mul_f32_e32 v38, v55, v80
	v_fmac_f32_e32 v38, v39, v79
	v_cvt_pk_bf16_f32 v38, v38, s0
	global_store_short v[52:53], v38, off offset:64
	v_or_b32_e32 v38, 42, v132
	v_lshl_or_b32 v54, v38, 5, v138
	v_ashrrev_i32_e32 v55, 31, v54
	v_lshlrev_b64 v[54:55], 2, v[54:55]
	v_lshl_add_u64 v[82:83], s[16:17], 0, v[54:55]
	v_lshl_add_u64 v[54:55], s[18:19], 0, v[54:55]
	v_mov_b32_e32 v81, v240
	s_nop 0
	v_mov_b32_e32 v82, v196
	v_mul_f32_e32 v39, v40, v82
	v_fma_f32 v39, v56, v81, -v39
	v_cvt_pk_bf16_f32 v54, v39, s0
	v_ashrrev_i32_e32 v39, 31, v38
	v_lshlrev_b64 v[38:39], 11, v[38:39]
	v_lshl_add_u64 v[38:39], v[130:131], 0, v[38:39]
	global_store_short v[38:39], v54, off
	v_mul_f32_e32 v54, v56, v82
	v_fmac_f32_e32 v54, v40, v81
	v_cvt_pk_bf16_f32 v40, v54, s0
	v_or_b32_e32 v54, 43, v132
	v_lshl_or_b32 v84, v54, 5, v138
	v_ashrrev_i32_e32 v85, 31, v84
	v_lshlrev_b64 v[84:85], 2, v[84:85]
	v_lshl_add_u64 v[86:87], s[16:17], 0, v[84:85]
	v_lshl_add_u64 v[84:85], s[18:19], 0, v[84:85]
	v_mov_b32_e32 v84, v197
	v_ashrrev_i32_e32 v55, 31, v54
	v_mov_b32_e32 v83, v241
	v_lshlrev_b64 v[54:55], 11, v[54:55]
	global_store_short v[38:39], v40, off offset:64
	v_lshl_add_u64 v[54:55], v[130:131], 0, v[54:55]
	v_mul_f32_e32 v40, v41, v84
	v_fma_f32 v40, v57, v83, -v40
	v_cvt_pk_bf16_f32 v40, v40, s0
	global_store_short v[54:55], v40, off
	v_mul_f32_e32 v40, v57, v84
	v_fmac_f32_e32 v40, v41, v83
	v_cvt_pk_bf16_f32 v40, v40, s0
	global_store_short v[54:55], v40, off offset:64
	v_or_b32_e32 v40, 48, v132
	v_lshl_or_b32 v56, v40, 5, v138
	v_ashrrev_i32_e32 v57, 31, v56
	v_lshlrev_b64 v[56:57], 2, v[56:57]
	v_lshl_add_u64 v[86:87], s[16:17], 0, v[56:57]
	v_lshl_add_u64 v[56:57], s[18:19], 0, v[56:57]
	v_mov_b32_e32 v85, v242
	s_nop 0
	v_mov_b32_e32 v86, v198
	v_mul_f32_e32 v41, v42, v86
	v_fma_f32 v41, v58, v85, -v41
	v_cvt_pk_bf16_f32 v56, v41, s0
	v_ashrrev_i32_e32 v41, 31, v40
	v_lshlrev_b64 v[40:41], 11, v[40:41]
	v_lshl_add_u64 v[40:41], v[130:131], 0, v[40:41]
	global_store_short v[40:41], v56, off
	v_mul_f32_e32 v56, v58, v86
	v_fmac_f32_e32 v56, v42, v85
	v_cvt_pk_bf16_f32 v42, v56, s0
	v_or_b32_e32 v56, 49, v132
	v_lshl_or_b32 v88, v56, 5, v138
	v_ashrrev_i32_e32 v89, 31, v88
	v_lshlrev_b64 v[88:89], 2, v[88:89]
	v_lshl_add_u64 v[90:91], s[16:17], 0, v[88:89]
	v_lshl_add_u64 v[88:89], s[18:19], 0, v[88:89]
	v_mov_b32_e32 v88, v199
	v_ashrrev_i32_e32 v57, 31, v56
	v_mov_b32_e32 v87, v243
	v_lshlrev_b64 v[56:57], 11, v[56:57]
	global_store_short v[40:41], v42, off offset:64
	v_lshl_add_u64 v[56:57], v[130:131], 0, v[56:57]
	v_mul_f32_e32 v42, v43, v88
	v_fma_f32 v42, v59, v87, -v42
	v_cvt_pk_bf16_f32 v42, v42, s0
	global_store_short v[56:57], v42, off
	v_mul_f32_e32 v42, v59, v88
	v_fmac_f32_e32 v42, v43, v87
	v_cvt_pk_bf16_f32 v42, v42, s0
	global_store_short v[56:57], v42, off offset:64
	v_or_b32_e32 v42, 50, v132
	v_lshl_or_b32 v58, v42, 5, v138
	v_ashrrev_i32_e32 v59, 31, v58
	v_lshlrev_b64 v[58:59], 2, v[58:59]
	v_lshl_add_u64 v[90:91], s[16:17], 0, v[58:59]
	v_lshl_add_u64 v[58:59], s[18:19], 0, v[58:59]
	v_mov_b32_e32 v89, v244
	s_nop 0
	v_mov_b32_e32 v90, v200
	v_mul_f32_e32 v43, v44, v90
	v_fma_f32 v43, v60, v89, -v43
	v_cvt_pk_bf16_f32 v58, v43, s0
	v_ashrrev_i32_e32 v43, 31, v42
	v_lshlrev_b64 v[42:43], 11, v[42:43]
	v_lshl_add_u64 v[42:43], v[130:131], 0, v[42:43]
	global_store_short v[42:43], v58, off
	v_mul_f32_e32 v58, v60, v90
	v_fmac_f32_e32 v58, v44, v89
	v_cvt_pk_bf16_f32 v44, v58, s0
	v_or_b32_e32 v58, 51, v132
	v_lshl_or_b32 v92, v58, 5, v138
	v_ashrrev_i32_e32 v93, 31, v92
	v_lshlrev_b64 v[92:93], 2, v[92:93]
	v_lshl_add_u64 v[94:95], s[16:17], 0, v[92:93]
	v_lshl_add_u64 v[92:93], s[18:19], 0, v[92:93]
	v_mov_b32_e32 v92, v201
	v_ashrrev_i32_e32 v59, 31, v58
	v_mov_b32_e32 v91, v245
	v_lshlrev_b64 v[58:59], 11, v[58:59]
	global_store_short v[42:43], v44, off offset:64
	v_lshl_add_u64 v[58:59], v[130:131], 0, v[58:59]
	v_mul_f32_e32 v44, v45, v92
	v_fma_f32 v44, v61, v91, -v44
	v_cvt_pk_bf16_f32 v44, v44, s0
	global_store_short v[58:59], v44, off
	v_mul_f32_e32 v44, v61, v92
	v_fmac_f32_e32 v44, v45, v91
	v_cvt_pk_bf16_f32 v44, v44, s0
	global_store_short v[58:59], v44, off offset:64
	v_or_b32_e32 v44, 56, v132
	v_lshl_or_b32 v60, v44, 5, v138
	v_ashrrev_i32_e32 v61, 31, v60
	v_lshlrev_b64 v[60:61], 2, v[60:61]
	v_lshl_add_u64 v[94:95], s[16:17], 0, v[60:61]
	v_lshl_add_u64 v[60:61], s[18:19], 0, v[60:61]
	v_mov_b32_e32 v93, v246
	s_nop 0
; DI bf16_t f2bf(float x) { return (bf16_t)(pack2(x, 0.f) & 0xffffu); }
; DI int crow(int i, int hh) { return (i & 3) + 8 * (i >> 2) + 4 * hh; }
;   DI void operator()(f32x16 (&acc)[2][4], int grow0, int gcol0, int lane, int w, char* lds) {
;     ...
;     const int part = gcol0 >> 10, cin = gcol0 & 1023;
;     if (part < 2) {
;       bf16_t* dst = part == 0 ? Q : K;
; #pragma unroll
;       for (int mt = 0; mt < 2; ++mt)
; #pragma unroll
;         for (int pr = 0; pr < 2; ++pr)
; #pragma unroll
;           for (int i = 0; i < 16; ++i) {
;             int row = grow0 + mt * 32 + crow(i, hh);
;             float c = cs[row * 32 + l31], s = sn[row * 32 + l31];
;             float x1 = acc[mt][2 * pr][i], x2 = acc[mt][2 * pr + 1][i];
;             int col = cin + pr * 64 + l31;
;             dst[(size_t)row * D_ + col] = f2bf(x1 * c - x2 * s);
;             dst[(size_t)row * D_ + col + 32] = f2bf(x2 * c + x1 * s);
;           }
	v_mov_b32_e32 v94, v202
	v_mul_f32_e32 v45, v46, v94
	v_fma_f32 v45, v62, v93, -v45
	v_cvt_pk_bf16_f32 v60, v45, s0
	v_ashrrev_i32_e32 v45, 31, v44
	v_lshlrev_b64 v[44:45], 11, v[44:45]
	v_lshl_add_u64 v[44:45], v[130:131], 0, v[44:45]
	global_store_short v[44:45], v60, off
	v_mul_f32_e32 v60, v62, v94
	v_fmac_f32_e32 v60, v46, v93
	v_cvt_pk_bf16_f32 v46, v60, s0
	v_or_b32_e32 v60, 57, v132
	v_lshl_or_b32 v96, v60, 5, v138
	v_ashrrev_i32_e32 v97, 31, v96
	v_lshlrev_b64 v[96:97], 2, v[96:97]
	v_lshl_add_u64 v[98:99], s[16:17], 0, v[96:97]
	v_lshl_add_u64 v[96:97], s[18:19], 0, v[96:97]
	v_mov_b32_e32 v96, v203
	v_ashrrev_i32_e32 v61, 31, v60
	v_mov_b32_e32 v95, v247
	v_lshlrev_b64 v[60:61], 11, v[60:61]
	global_store_short v[44:45], v46, off offset:64
	v_lshl_add_u64 v[60:61], v[130:131], 0, v[60:61]
	v_mul_f32_e32 v46, v47, v96
	v_fma_f32 v46, v63, v95, -v46
	v_cvt_pk_bf16_f32 v46, v46, s0
	global_store_short v[60:61], v46, off
	v_mul_f32_e32 v46, v63, v96
	v_fmac_f32_e32 v46, v47, v95
	v_cvt_pk_bf16_f32 v46, v46, s0
	global_store_short v[60:61], v46, off offset:64
	v_or_b32_e32 v46, 58, v132
	v_lshl_or_b32 v62, v46, 5, v138
	v_ashrrev_i32_e32 v63, 31, v62
	v_lshlrev_b64 v[62:63], 2, v[62:63]
	v_lshl_add_u64 v[98:99], s[16:17], 0, v[62:63]
	v_lshl_add_u64 v[62:63], s[18:19], 0, v[62:63]
	v_mov_b32_e32 v97, v248
	s_nop 0
	v_mov_b32_e32 v98, v204
	v_mul_f32_e32 v47, v48, v98
	v_fma_f32 v47, v64, v97, -v47
	v_cvt_pk_bf16_f32 v62, v47, s0
	v_ashrrev_i32_e32 v47, 31, v46
	v_lshlrev_b64 v[46:47], 11, v[46:47]
	v_lshl_add_u64 v[46:47], v[130:131], 0, v[46:47]
	global_store_short v[46:47], v62, off
	v_mul_f32_e32 v62, v64, v98
	v_fmac_f32_e32 v62, v48, v97
	v_cvt_pk_bf16_f32 v48, v62, s0
	v_or_b32_e32 v62, 59, v132
	v_lshl_or_b32 v100, v62, 5, v138
	v_ashrrev_i32_e32 v101, 31, v100
	v_lshlrev_b64 v[100:101], 2, v[100:101]
	v_lshl_add_u64 v[102:103], s[16:17], 0, v[100:101]
	v_lshl_add_u64 v[100:101], s[18:19], 0, v[100:101]
	v_mov_b32_e32 v64, v205
	v_mul_f32_e32 v63, v49, v64
	global_store_short v[46:47], v48, off offset:64
	v_mov_b32_e32 v48, v249
	v_fma_f32 v63, v65, v48, -v63
	v_cvt_pk_bf16_f32 v99, v63, s0
	v_ashrrev_i32_e32 v63, 31, v62
	v_mul_f32_e32 v65, v65, v64
	v_lshlrev_b64 v[62:63], 11, v[62:63]
	v_fmac_f32_e32 v65, v49, v48
	v_lshl_add_u64 v[62:63], v[130:131], 0, v[62:63]
	v_cvt_pk_bf16_f32 v49, v65, s0
	global_store_short v[62:63], v49, off offset:64
	v_mul_f32_e32 v49, v2, v70
	v_fma_f32 v49, v18, v0, -v49
	v_mul_f32_e32 v18, v18, v70
	v_fmac_f32_e32 v18, v2, v0
	v_cvt_pk_bf16_f32 v0, v18, s0
	global_store_short v[66:67], v0, off offset:192
	v_mul_f32_e32 v0, v3, v72
	v_fma_f32 v0, v19, v71, -v0
	v_cvt_pk_bf16_f32 v0, v0, s0
	global_store_short v[68:69], v0, off offset:128
	v_mul_f32_e32 v0, v19, v72
	v_fmac_f32_e32 v0, v3, v71
	v_cvt_pk_bf16_f32 v0, v0, s0
	global_store_short v[68:69], v0, off offset:192
	v_mul_f32_e32 v0, v4, v74
	v_fma_f32 v0, v20, v73, -v0
	v_cvt_pk_bf16_f32 v0, v0, s0
	global_store_short v[34:35], v0, off offset:128
	v_mul_f32_e32 v0, v20, v74
	v_fmac_f32_e32 v0, v4, v73
	v_cvt_pk_bf16_f32 v0, v0, s0
	global_store_short v[34:35], v0, off offset:192
	v_mul_f32_e32 v0, v5, v76
	v_fma_f32 v0, v21, v75, -v0
	v_cvt_pk_bf16_f32 v0, v0, s0
	global_store_short v[50:51], v0, off offset:128
	v_mul_f32_e32 v0, v21, v76
	v_fmac_f32_e32 v0, v5, v75
	v_cvt_pk_bf16_f32 v0, v0, s0
	global_store_short v[50:51], v0, off offset:192
	v_mul_f32_e32 v0, v6, v78
	v_fma_f32 v0, v22, v77, -v0
	v_cvt_pk_bf16_f32 v0, v0, s0
	global_store_short v[36:37], v0, off offset:128
	v_mul_f32_e32 v0, v22, v78
	v_fmac_f32_e32 v0, v6, v77
	v_cvt_pk_bf16_f32 v0, v0, s0
	global_store_short v[36:37], v0, off offset:192
	v_mul_f32_e32 v0, v7, v80
	v_fma_f32 v0, v23, v79, -v0
	v_cvt_pk_bf16_f32 v0, v0, s0
	global_store_short v[52:53], v0, off offset:128
	v_mul_f32_e32 v0, v23, v80
	v_fmac_f32_e32 v0, v7, v79
	v_cvt_pk_bf16_f32 v0, v0, s0
	global_store_short v[52:53], v0, off offset:192
	v_mul_f32_e32 v0, v8, v82
	v_fma_f32 v0, v24, v81, -v0
	v_cvt_pk_bf16_f32 v0, v0, s0
	global_store_short v[38:39], v0, off offset:128
	v_mul_f32_e32 v0, v24, v82
	v_fmac_f32_e32 v0, v8, v81
	v_cvt_pk_bf16_f32 v0, v0, s0
	global_store_short v[38:39], v0, off offset:192
	v_mul_f32_e32 v0, v9, v84
	v_fma_f32 v0, v25, v83, -v0
	v_cvt_pk_bf16_f32 v0, v0, s0
	global_store_short v[54:55], v0, off offset:128
	v_mul_f32_e32 v0, v25, v84
	v_fmac_f32_e32 v0, v9, v83
	v_cvt_pk_bf16_f32 v0, v0, s0
	global_store_short v[54:55], v0, off offset:192
	v_mul_f32_e32 v0, v10, v86
	v_fma_f32 v0, v26, v85, -v0
	v_cvt_pk_bf16_f32 v0, v0, s0
	global_store_short v[40:41], v0, off offset:128
	v_mul_f32_e32 v0, v26, v86
	v_fmac_f32_e32 v0, v10, v85
	v_cvt_pk_bf16_f32 v0, v0, s0
	global_store_short v[40:41], v0, off offset:192
	v_mul_f32_e32 v0, v11, v88
	v_fma_f32 v0, v27, v87, -v0
	v_cvt_pk_bf16_f32 v0, v0, s0
	global_store_short v[56:57], v0, off offset:128
	v_mul_f32_e32 v0, v27, v88
	v_fmac_f32_e32 v0, v11, v87
	v_cvt_pk_bf16_f32 v0, v0, s0
	global_store_short v[56:57], v0, off offset:192
	v_mul_f32_e32 v0, v12, v90
	v_fma_f32 v0, v28, v89, -v0
	v_cvt_pk_bf16_f32 v0, v0, s0
	global_store_short v[42:43], v0, off offset:128
	v_mul_f32_e32 v0, v28, v90
	v_fmac_f32_e32 v0, v12, v89
	v_cvt_pk_bf16_f32 v0, v0, s0
	global_store_short v[42:43], v0, off offset:192
	v_mul_f32_e32 v0, v13, v92
	v_fma_f32 v0, v29, v91, -v0
	v_cvt_pk_bf16_f32 v0, v0, s0
	global_store_short v[58:59], v0, off offset:128
	v_mul_f32_e32 v0, v29, v92
	v_fmac_f32_e32 v0, v13, v91
	v_cvt_pk_bf16_f32 v0, v0, s0
	global_store_short v[58:59], v0, off offset:192
	v_mul_f32_e32 v0, v14, v94
	v_fma_f32 v0, v30, v93, -v0
	v_cvt_pk_bf16_f32 v0, v0, s0
	global_store_short v[44:45], v0, off offset:128
	v_mul_f32_e32 v0, v30, v94
	v_fmac_f32_e32 v0, v14, v93
	v_cvt_pk_bf16_f32 v0, v0, s0
	global_store_short v[44:45], v0, off offset:192
	v_mul_f32_e32 v0, v15, v96
	v_fma_f32 v0, v31, v95, -v0
	v_cvt_pk_bf16_f32 v0, v0, s0
	global_store_short v[60:61], v0, off offset:128
	v_mul_f32_e32 v0, v31, v96
	v_fmac_f32_e32 v0, v15, v95
	v_cvt_pk_bf16_f32 v0, v0, s0
	global_store_short v[60:61], v0, off offset:192
	v_mul_f32_e32 v0, v16, v98
	v_fma_f32 v0, v32, v97, -v0
	v_cvt_pk_bf16_f32 v0, v0, s0
	global_store_short v[46:47], v0, off offset:128
	v_mul_f32_e32 v0, v32, v98
	v_fmac_f32_e32 v0, v16, v97
	v_cvt_pk_bf16_f32 v0, v0, s0
	global_store_short v[46:47], v0, off offset:192
	v_mul_f32_e32 v0, v17, v64
	v_fma_f32 v0, v33, v48, -v0
	v_cvt_pk_bf16_f32 v0, v0, s0
	global_store_short v[62:63], v0, off offset:128
	v_mul_f32_e32 v0, v33, v64
	v_fmac_f32_e32 v0, v17, v48
	v_cvt_pk_bf16_f32 v49, v49, s0
	v_cvt_pk_bf16_f32 v0, v0, s0
	global_store_short v[62:63], v99, off
	global_store_short v[66:67], v49, off offset:128
	global_store_short v[62:63], v0, off offset:192
	s_branch .LBB0_515
